# attention K-row prefetch; layer-0 seam uses the XCD barrier instead of cg grid.sync; RW2 redundant vmcnt(0) removed
# speedup vs baseline: 1.0067x; 1.0067x over previous
; #define GRID_SYNC() do { for (int r_ = 0; r_ < REP_SYNC; ++r_) xcd_barrier(xbar); } while (0)
; __global__ void __launch_bounds__(NTHR, 2) fwd_megakernel(Args a) {
;     ...
;         if (layer == 0) grid.sync();
;         else GRID_SYNC();
.LBB0_186:
	s_cmp_eq_u32 s40, 0
	s_cselect_b64 s[4:5], -1, 0
	v_writelane_b32 v254, s4, 29
	s_cmp_lg_u32 s40, 0
	s_cselect_b64 s[6:7], -1, 0
	v_writelane_b32 v254, s5, 30
	v_writelane_b32 v254, s6, 31
	s_mov_b64 s[4:5], -1
	s_and_b64 vcc, exec, s[6:7]
	v_writelane_b32 v254, s7, 32
	s_branch .LBB0_189
	s_and_b64 vcc, exec, s[4:5]
	s_cbranch_vccnz .LBB0_242

; #define PG8_STAGE(bufoff, gbase, voff) do { _Pragma("unroll") for (int _i = 0; _i < 2; ++_i) \
;         __builtin_amdgcn_global_load_lds((const unsigned*)((const char*)(gbase) + (voff)[_i]), (PG8_LAS unsigned*)(lds + (bufoff) + ldsw + _i * 8192), 16, 0, 0); } while (0)
; #define PG8_LDA(dst, b, h) do { _Pragma("unroll") for (int m = 0; m < 4; ++m) _Pragma("unroll") for (int k = 0; k < 2; ++k) dst[m][k] = *(const PG8_LAS bf16x8*)(lds + PG8_SA(b, h) + aoff + m * 2048 + k * 1024); } while (0)
; #define PG8_LDB(dst, b, h) do { _Pragma("unroll") for (int n = 0; n < 2; ++n) _Pragma("unroll") for (int k = 0; k < 2; ++k) dst[n][k] = *(const PG8_LAS bf16x8*)(lds + PG8_SB(b, h) + boff + n * 2048 + k * 1024); } while (0)
; template <class Epi, class Sched, bool ALIGN_EPI = false, bool SP2 = false>
; __device__ __forceinline__ void gemm_phase(PG8_LAS unsigned char* lds, const Gemm g, const Sched& S, const Epi& E) {
;     ...
;         for (int t = 0; t < nt; t += 2) {
;             const bool last = (t == nt - 2);
;             const char* a1 = cA + (size_t)(t + 1) * kstep;
;             const char* a2 = last ? nA : cA + (size_t)(t + 2) * kstep; const char* b2 = last ? nB : cB + (size_t)(t + 2) * kstep;
;             const char* a3 = a2 + kstep; const char* b3 = b2 + kstep;
;             if (last && has_next) S.a_ready(nxt);
;             if constexpr (SP2) {
;             PG8_LDB(B0, 0, 0); PG8_LDB(B1, 0, 1); PG8_SCHED; PG8_LDA(At, 0, 0); PG8_STAGE(PG8_SA(1, 1), a1 + hstep, voffA);
;             PG8_WAIT_V(8); PG8_WAIT_L(0); PG8_BAR; PG8_MMA(0, 0, At, B0); PG8_MMA(0, 1, At, B1); PG8_BAR; PG8_SCHED;
;             PG8_LDA(At, 0, 1); PG8_STAGE(PG8_SB(0, 0), b2, voffB); PG8_STAGE(PG8_SB(0, 1), b2 + hstep, voffB); PG8_STAGE(PG8_SA(0, 0), a2, voffA);
;             PG8_WAIT_V(8); PG8_WAIT_L(0); PG8_BAR; PG8_MMA(1, 0, At, B0); PG8_MMA(1, 1, At, B1); PG8_BAR; PG8_SCHED;
;             PG8_LDB(B0, 1, 0); PG8_LDB(B1, 1, 1); PG8_SCHED; PG8_LDA(At, 1, 0); PG8_STAGE(PG8_SA(0, 1), a2 + hstep, voffA);
;             PG8_WAIT_V(8); PG8_WAIT_L(0); PG8_BAR; PG8_MMA(0, 0, At, B0); PG8_MMA(0, 1, At, B1); PG8_BAR; PG8_SCHED;
;             PG8_LDA(At, 1, 1); PG8_STAGE(PG8_SB(1, 0), b3, voffB); PG8_STAGE(PG8_SB(1, 1), b3 + hstep, voffB); PG8_STAGE(PG8_SA(1, 0), a3, voffA);
;             PG8_WAIT_V(8); PG8_WAIT_L(0); PG8_BAR; PG8_MMA(1, 0, At, B0); PG8_MMA(1, 1, At, B1); PG8_BAR; PG8_SCHED;
.LBB0_380:
	s_add_i32 s40, s6, 2
	s_add_u32 s41, s4, 0x80
	s_addc_u32 s7, s5, 0
	s_add_i32 s43, 0, 0x10000
	s_cmp_eq_u32 s60, s6
	s_cselect_b32 s7, s55, s7
	s_cselect_b32 s6, s54, s41
	v_add_u32_e32 v34, s43, v180
	s_cselect_b32 s69, s57, s9
	s_cselect_b32 s68, s56, s8
	s_add_i32 s41, 0, 0x14000
	ds_read_b128 v[44:47], v34
	ds_read_b128 v[48:51], v34 offset:1024
	ds_read_b128 v[52:55], v34 offset:2048
	ds_read_b128 v[56:59], v34 offset:3072
	v_add_u32_e32 v34, s41, v180
	ds_read_b128 v[158:161], v34
	ds_read_b128 v[162:165], v34 offset:1024
	ds_read_b128 v[166:169], v34 offset:2048
	ds_read_b128 v[170:173], v34 offset:3072
	v_lshl_add_u64 v[178:179], s[4:5], 0, v[154:155]
	s_add_i32 m0, s15, 0xc000
	ds_read_b128 v[174:177], v182
	ds_read_b128 v[184:187], v182 offset:1024
	ds_read_b128 v[188:191], v182 offset:2048
	ds_read_b128 v[192:195], v182 offset:3072
	ds_read_b128 v[196:199], v182 offset:4096
	ds_read_b128 v[200:203], v182 offset:5120
	ds_read_b128 v[204:207], v182 offset:6144
	ds_read_b128 v[208:211], v182 offset:7168
	global_load_lds_dwordx4 v[178:179], off
	v_lshl_add_u64 v[178:179], s[4:5], 0, v[156:157]
	s_add_i32 m0, s15, 0xe000
	s_nop 0
	global_load_lds_dwordx4 v[178:179], off
	s_waitcnt vmcnt(8)
	s_waitcnt lgkmcnt(0)
	s_barrier
	s_setprio 1
	s_waitcnt lgkmcnt(0)
	v_mfma_f32_16x16x32_bf16 v[140:143], v[44:47], v[174:177], v[140:143]
	v_mfma_f32_16x16x32_bf16 v[144:147], v[52:55], v[174:177], v[144:147]
	v_mfma_f32_16x16x32_bf16 v[124:127], v[44:47], v[188:191], v[124:127]
	v_mfma_f32_16x16x32_bf16 v[128:131], v[52:55], v[188:191], v[128:131]
	v_mfma_f32_16x16x32_bf16 v[108:111], v[44:47], v[196:199], v[108:111]
	v_mfma_f32_16x16x32_bf16 v[112:115], v[52:55], v[196:199], v[112:115]
	v_mfma_f32_16x16x32_bf16 v[92:95], v[44:47], v[204:207], v[92:95]
	v_mfma_f32_16x16x32_bf16 v[96:99], v[52:55], v[204:207], v[96:99]
	v_mfma_f32_16x16x32_bf16 v[140:143], v[48:51], v[184:187], v[140:143]
	v_mfma_f32_16x16x32_bf16 v[144:147], v[56:59], v[184:187], v[144:147]
	v_mfma_f32_16x16x32_bf16 v[124:127], v[48:51], v[192:195], v[124:127]
	v_mfma_f32_16x16x32_bf16 v[128:131], v[56:59], v[192:195], v[128:131]
	v_mfma_f32_16x16x32_bf16 v[108:111], v[48:51], v[200:203], v[108:111]
	v_mfma_f32_16x16x32_bf16 v[112:115], v[56:59], v[200:203], v[112:115]
	v_mfma_f32_16x16x32_bf16 v[92:95], v[48:51], v[208:211], v[92:95]
	v_mfma_f32_16x16x32_bf16 v[96:99], v[56:59], v[208:211], v[96:99]
	s_setprio 0
	s_setprio 1
	v_mfma_f32_16x16x32_bf16 v[132:135], v[158:161], v[174:177], v[132:135]
	v_mfma_f32_16x16x32_bf16 v[136:139], v[166:169], v[174:177], v[136:139]
	v_mfma_f32_16x16x32_bf16 v[116:119], v[158:161], v[188:191], v[116:119]
	v_mfma_f32_16x16x32_bf16 v[120:123], v[166:169], v[188:191], v[120:123]
	v_mfma_f32_16x16x32_bf16 v[100:103], v[158:161], v[196:199], v[100:103]
	v_mfma_f32_16x16x32_bf16 v[104:107], v[166:169], v[196:199], v[104:107]
	v_mfma_f32_16x16x32_bf16 v[84:87], v[158:161], v[204:207], v[84:87]
	v_mfma_f32_16x16x32_bf16 v[88:91], v[166:169], v[204:207], v[88:91]
	v_mfma_f32_16x16x32_bf16 v[132:135], v[162:165], v[184:187], v[132:135]
	v_mfma_f32_16x16x32_bf16 v[136:139], v[170:173], v[184:187], v[136:139]
	v_mfma_f32_16x16x32_bf16 v[116:119], v[162:165], v[192:195], v[116:119]
	v_mfma_f32_16x16x32_bf16 v[120:123], v[170:173], v[192:195], v[120:123]
	v_mfma_f32_16x16x32_bf16 v[100:103], v[162:165], v[200:203], v[100:103]
	v_mfma_f32_16x16x32_bf16 v[104:107], v[170:173], v[200:203], v[104:107]
	v_mfma_f32_16x16x32_bf16 v[84:87], v[162:165], v[208:211], v[84:87]
	v_mfma_f32_16x16x32_bf16 v[88:91], v[170:173], v[208:211], v[88:91]
	s_setprio 0
	s_barrier
	s_add_i32 s43, s43, s14
	v_lshl_add_u64 v[178:179], s[68:69], 0, v[150:151]
	s_mov_b32 m0, s43
	ds_read_b128 v[174:177], v182 offset:16384
	ds_read_b128 v[184:187], v182 offset:17408
	ds_read_b128 v[188:191], v182 offset:18432
	ds_read_b128 v[192:195], v182 offset:19456
	ds_read_b128 v[196:199], v182 offset:20480
	ds_read_b128 v[200:203], v182 offset:21504
	ds_read_b128 v[204:207], v182 offset:22528
	ds_read_b128 v[208:211], v182 offset:23552
	global_load_lds_dwordx4 v[178:179], off
	s_add_i32 m0, s43, 0x2000
	v_lshl_add_u64 v[212:213], s[68:69], 0, v[32:33]
	s_add_u32 s68, s68, s44
	s_addc_u32 s69, s69, s45
	s_add_i32 s41, s41, s14
	global_load_lds_dwordx4 v[212:213], off
	v_lshl_add_u64 v[214:215], s[68:69], 0, v[150:151]
	s_mov_b32 m0, s41
	v_lshl_add_u64 v[216:217], s[68:69], 0, v[32:33]
	global_load_lds_dwordx4 v[214:215], off
	s_add_i32 m0, s41, 0x2000
	v_lshl_add_u64 v[218:219], s[6:7], 0, v[152:153]
	global_load_lds_dwordx4 v[216:217], off
	s_mov_b32 m0, s15
	v_lshl_add_u64 v[220:221], s[6:7], 0, v[148:149]
	global_load_lds_dwordx4 v[218:219], off
	s_mov_b32 m0, s16
	s_nop 0
	global_load_lds_dwordx4 v[220:221], off
	s_waitcnt vmcnt(8)
	s_waitcnt lgkmcnt(0)
	s_barrier
; #define PG8_STAGE(bufoff, gbase, voff) do { _Pragma("unroll") for (int _i = 0; _i < 2; ++_i) \
;         __builtin_amdgcn_global_load_lds((const unsigned*)((const char*)(gbase) + (voff)[_i]), (PG8_LAS unsigned*)(lds + (bufoff) + ldsw + _i * 8192), 16, 0, 0); } while (0)
; #define PG8_LDA(dst, b, h) do { _Pragma("unroll") for (int m = 0; m < 4; ++m) _Pragma("unroll") for (int k = 0; k < 2; ++k) dst[m][k] = *(const PG8_LAS bf16x8*)(lds + PG8_SA(b, h) + aoff + m * 2048 + k * 1024); } while (0)
; #define PG8_LDB(dst, b, h) do { _Pragma("unroll") for (int n = 0; n < 2; ++n) _Pragma("unroll") for (int k = 0; k < 2; ++k) dst[n][k] = *(const PG8_LAS bf16x8*)(lds + PG8_SB(b, h) + boff + n * 2048 + k * 1024); } while (0)
; #define PG8_MMA(ai, bj, At, Bt) do { __builtin_amdgcn_s_setprio(1); _Pragma("unroll") for (int m = 0; m < 4; ++m) _Pragma("unroll") for (int n = 0; n < 2; ++n) _Pragma("unroll") for (int k = 0; k < 2; ++k) \
;         acc[ai][bj][m][n] = __builtin_amdgcn_mfma_f32_16x16x32_bf16(Bt[n][k], At[m][k], acc[ai][bj][m][n], 0, 0, 0); __builtin_amdgcn_s_setprio(0); } while (0)
; #define PG8_WAIT_V(n) asm volatile("s_waitcnt vmcnt(" #n ")" ::: "memory")
; #define PG8_WAIT_L(n) asm volatile("s_waitcnt lgkmcnt(" #n ")" ::: "memory")
; #define PG8_BAR __builtin_amdgcn_s_barrier()
; #define PG8_SCHED __builtin_amdgcn_sched_barrier(0)
; template <class Epi, class Sched, bool ALIGN_EPI = false, bool SP2 = false>
; __device__ __forceinline__ void gemm_phase(PG8_LAS unsigned char* lds, const Gemm g, const Sched& S, const Epi& E) {
;     ...
;             PG8_WAIT_V(8); PG8_WAIT_L(0); PG8_BAR; PG8_MMA(1, 0, At, B0); PG8_MMA(1, 1, At, B1); PG8_BAR; PG8_SCHED;
;             PG8_LDB(B0, 1, 0); PG8_LDB(B1, 1, 1); PG8_SCHED; PG8_LDA(At, 1, 0); PG8_STAGE(PG8_SA(0, 1), a2 + hstep, voffA);
;             PG8_WAIT_V(8); PG8_WAIT_L(0); PG8_BAR; PG8_MMA(0, 0, At, B0); PG8_MMA(0, 1, At, B1); PG8_BAR; PG8_SCHED;
;             PG8_LDA(At, 1, 1); PG8_STAGE(PG8_SB(1, 0), b3, voffB); PG8_STAGE(PG8_SB(1, 1), b3 + hstep, voffB); PG8_STAGE(PG8_SA(1, 0), a3, voffA);
;             PG8_WAIT_V(8); PG8_WAIT_L(0); PG8_BAR; PG8_MMA(1, 0, At, B0); PG8_MMA(1, 1, At, B1); PG8_BAR; PG8_SCHED;
	s_setprio 1
	s_waitcnt lgkmcnt(0)
	v_mfma_f32_16x16x32_bf16 v[76:79], v[44:47], v[174:177], v[76:79]
	v_mfma_f32_16x16x32_bf16 v[80:83], v[52:55], v[174:177], v[80:83]
	v_mfma_f32_16x16x32_bf16 v[60:63], v[44:47], v[188:191], v[60:63]
	v_mfma_f32_16x16x32_bf16 v[64:67], v[52:55], v[188:191], v[64:67]
	v_mfma_f32_16x16x32_bf16 v[24:27], v[44:47], v[196:199], v[24:27]
	v_mfma_f32_16x16x32_bf16 v[28:31], v[52:55], v[196:199], v[28:31]
	v_mfma_f32_16x16x32_bf16 v[8:11], v[44:47], v[204:207], v[8:11]
	v_mfma_f32_16x16x32_bf16 v[12:15], v[52:55], v[204:207], v[12:15]
	v_mfma_f32_16x16x32_bf16 v[76:79], v[48:51], v[184:187], v[76:79]
	v_mfma_f32_16x16x32_bf16 v[80:83], v[56:59], v[184:187], v[80:83]
	v_mfma_f32_16x16x32_bf16 v[60:63], v[48:51], v[192:195], v[60:63]
	v_mfma_f32_16x16x32_bf16 v[64:67], v[56:59], v[192:195], v[64:67]
	v_mfma_f32_16x16x32_bf16 v[24:27], v[48:51], v[200:203], v[24:27]
	v_mfma_f32_16x16x32_bf16 v[28:31], v[56:59], v[200:203], v[28:31]
	v_mfma_f32_16x16x32_bf16 v[8:11], v[48:51], v[208:211], v[8:11]
	v_mfma_f32_16x16x32_bf16 v[12:15], v[56:59], v[208:211], v[12:15]
	s_setprio 0
	s_setprio 1
	v_mfma_f32_16x16x32_bf16 v[36:39], v[158:161], v[188:191], v[36:39]
	v_mfma_f32_16x16x32_bf16 v[40:43], v[166:169], v[188:191], v[40:43]
	v_mfma_f32_16x16x32_bf16 v[16:19], v[158:161], v[196:199], v[16:19]
	v_mfma_f32_16x16x32_bf16 v[20:23], v[166:169], v[196:199], v[20:23]
	v_mfma_f32_16x16x32_bf16 v[0:3], v[158:161], v[204:207], v[0:3]
	v_mfma_f32_16x16x32_bf16 v[4:7], v[166:169], v[204:207], v[4:7]
	v_mfma_f32_16x16x32_bf16 v[44:47], v[158:161], v[174:177], v[68:71]
	v_mfma_f32_16x16x32_bf16 v[48:51], v[166:169], v[174:177], v[72:75]
	v_mfma_f32_16x16x32_bf16 v[36:39], v[162:165], v[192:195], v[36:39]
	v_mfma_f32_16x16x32_bf16 v[40:43], v[170:173], v[192:195], v[40:43]
	v_mfma_f32_16x16x32_bf16 v[16:19], v[162:165], v[200:203], v[16:19]
	v_mfma_f32_16x16x32_bf16 v[20:23], v[170:173], v[200:203], v[20:23]
	v_mfma_f32_16x16x32_bf16 v[0:3], v[162:165], v[208:211], v[0:3]
	v_mfma_f32_16x16x32_bf16 v[4:7], v[170:173], v[208:211], v[4:7]
	v_mfma_f32_16x16x32_bf16 v[44:47], v[162:165], v[184:187], v[44:47]
	v_mfma_f32_16x16x32_bf16 v[48:51], v[170:173], v[184:187], v[48:51]
	s_setprio 0
	s_barrier
	s_add_i32 s41, 0, 0x18000
	v_add_u32_e32 v34, s41, v180
	s_add_i32 s43, 0, 0x1c000
	ds_read_b128 v[52:55], v34
	ds_read_b128 v[56:59], v34 offset:1024
	ds_read_b128 v[68:71], v34 offset:2048
	ds_read_b128 v[72:75], v34 offset:3072
	v_add_u32_e32 v34, s43, v180
	ds_read_b128 v[158:161], v34
	ds_read_b128 v[162:165], v34 offset:1024
	ds_read_b128 v[166:169], v34 offset:2048
	ds_read_b128 v[170:173], v34 offset:3072
	s_add_u32 s6, s6, s44
	s_addc_u32 s7, s7, s45
	s_mov_b32 m0, s17
	v_lshl_add_u64 v[222:223], s[6:7], 0, v[152:153]
	ds_read_b128 v[174:177], v182 offset:32768
	ds_read_b128 v[184:187], v182 offset:33792
	ds_read_b128 v[188:191], v182 offset:34816
	ds_read_b128 v[192:195], v182 offset:35840
	ds_read_b128 v[196:199], v182 offset:36864
	ds_read_b128 v[200:203], v182 offset:37888
	ds_read_b128 v[204:207], v182 offset:38912
	ds_read_b128 v[208:211], v182 offset:39936
	global_load_lds_dwordx4 v[222:223], off
	v_lshl_add_u64 v[222:223], s[6:7], 0, v[148:149]
	s_mov_b32 m0, s18
	s_nop 0
	global_load_lds_dwordx4 v[222:223], off
	s_waitcnt vmcnt(8)
	s_waitcnt lgkmcnt(0)
	s_barrier
	s_setprio 1
	s_waitcnt lgkmcnt(0)
	v_mfma_f32_16x16x32_bf16 v[140:143], v[52:55], v[174:177], v[140:143]
	v_mfma_f32_16x16x32_bf16 v[144:147], v[68:71], v[174:177], v[144:147]
	v_mfma_f32_16x16x32_bf16 v[124:127], v[52:55], v[188:191], v[124:127]
	v_mfma_f32_16x16x32_bf16 v[128:131], v[68:71], v[188:191], v[128:131]
	v_mfma_f32_16x16x32_bf16 v[108:111], v[52:55], v[196:199], v[108:111]
	v_mfma_f32_16x16x32_bf16 v[112:115], v[68:71], v[196:199], v[112:115]
	v_mfma_f32_16x16x32_bf16 v[92:95], v[52:55], v[204:207], v[92:95]
	v_mfma_f32_16x16x32_bf16 v[96:99], v[68:71], v[204:207], v[96:99]
	v_mfma_f32_16x16x32_bf16 v[140:143], v[56:59], v[184:187], v[140:143]
	v_mfma_f32_16x16x32_bf16 v[144:147], v[72:75], v[184:187], v[144:147]
	v_mfma_f32_16x16x32_bf16 v[124:127], v[56:59], v[192:195], v[124:127]
	v_mfma_f32_16x16x32_bf16 v[128:131], v[72:75], v[192:195], v[128:131]
	v_mfma_f32_16x16x32_bf16 v[108:111], v[56:59], v[200:203], v[108:111]
	v_mfma_f32_16x16x32_bf16 v[112:115], v[72:75], v[200:203], v[112:115]
	v_mfma_f32_16x16x32_bf16 v[92:95], v[56:59], v[208:211], v[92:95]
	v_mfma_f32_16x16x32_bf16 v[96:99], v[72:75], v[208:211], v[96:99]
	s_setprio 0
	s_setprio 1
	v_mfma_f32_16x16x32_bf16 v[132:135], v[158:161], v[174:177], v[132:135]
	v_mfma_f32_16x16x32_bf16 v[136:139], v[166:169], v[174:177], v[136:139]
	v_mfma_f32_16x16x32_bf16 v[116:119], v[158:161], v[188:191], v[116:119]
	v_mfma_f32_16x16x32_bf16 v[120:123], v[166:169], v[188:191], v[120:123]
	v_mfma_f32_16x16x32_bf16 v[100:103], v[158:161], v[196:199], v[100:103]
	v_mfma_f32_16x16x32_bf16 v[104:107], v[166:169], v[196:199], v[104:107]
	v_mfma_f32_16x16x32_bf16 v[84:87], v[158:161], v[204:207], v[84:87]
	v_mfma_f32_16x16x32_bf16 v[88:91], v[166:169], v[204:207], v[88:91]
	v_mfma_f32_16x16x32_bf16 v[132:135], v[162:165], v[184:187], v[132:135]
	v_mfma_f32_16x16x32_bf16 v[136:139], v[170:173], v[184:187], v[136:139]
	v_mfma_f32_16x16x32_bf16 v[116:119], v[162:165], v[192:195], v[116:119]
	v_mfma_f32_16x16x32_bf16 v[120:123], v[170:173], v[192:195], v[120:123]
	v_mfma_f32_16x16x32_bf16 v[100:103], v[162:165], v[200:203], v[100:103]
	v_mfma_f32_16x16x32_bf16 v[104:107], v[170:173], v[200:203], v[104:107]
	v_mfma_f32_16x16x32_bf16 v[84:87], v[162:165], v[208:211], v[84:87]
	v_mfma_f32_16x16x32_bf16 v[88:91], v[170:173], v[208:211], v[88:91]
	s_setprio 0
	s_barrier
; #define PG8_STAGE(bufoff, gbase, voff) do { _Pragma("unroll") for (int _i = 0; _i < 2; ++_i) \
;         __builtin_amdgcn_global_load_lds((const unsigned*)((const char*)(gbase) + (voff)[_i]), (PG8_LAS unsigned*)(lds + (bufoff) + ldsw + _i * 8192), 16, 0, 0); } while (0)
; #define PG8_LDA(dst, b, h) do { _Pragma("unroll") for (int m = 0; m < 4; ++m) _Pragma("unroll") for (int k = 0; k < 2; ++k) dst[m][k] = *(const PG8_LAS bf16x8*)(lds + PG8_SA(b, h) + aoff + m * 2048 + k * 1024); } while (0)
; #define PG8_MMA(ai, bj, At, Bt) do { __builtin_amdgcn_s_setprio(1); _Pragma("unroll") for (int m = 0; m < 4; ++m) _Pragma("unroll") for (int n = 0; n < 2; ++n) _Pragma("unroll") for (int k = 0; k < 2; ++k) \
;         acc[ai][bj][m][n] = __builtin_amdgcn_mfma_f32_16x16x32_bf16(Bt[n][k], At[m][k], acc[ai][bj][m][n], 0, 0, 0); __builtin_amdgcn_s_setprio(0); } while (0)
; #define PG8_WAIT_V(n) asm volatile("s_waitcnt vmcnt(" #n ")" ::: "memory")
; #define PG8_WAIT_L(n) asm volatile("s_waitcnt lgkmcnt(" #n ")" ::: "memory")
; #define PG8_BAR __builtin_amdgcn_s_barrier()
; #define PG8_SCHED __builtin_amdgcn_sched_barrier(0)
; template <class Epi, class Sched, bool ALIGN_EPI = false, bool SP2 = false>
; __device__ __forceinline__ void gemm_phase(PG8_LAS unsigned char* lds, const Gemm g, const Sched& S, const Epi& E) {
;     ...
;         for (int t = 0; t < nt; t += 2) {
;             const bool last = (t == nt - 2);
;             const char* a1 = cA + (size_t)(t + 1) * kstep;
;             const char* a2 = last ? nA : cA + (size_t)(t + 2) * kstep; const char* b2 = last ? nB : cB + (size_t)(t + 2) * kstep;
;             const char* a3 = a2 + kstep; const char* b3 = b2 + kstep;
;     ...
;             PG8_LDA(At, 1, 1); PG8_STAGE(PG8_SB(1, 0), b3, voffB); PG8_STAGE(PG8_SB(1, 1), b3 + hstep, voffB); PG8_STAGE(PG8_SA(1, 0), a3, voffA);
;             PG8_WAIT_V(8); PG8_WAIT_L(0); PG8_BAR; PG8_MMA(1, 0, At, B0); PG8_MMA(1, 1, At, B1); PG8_BAR; PG8_SCHED;
	s_add_i32 s6, s41, s14
	v_lshl_add_u64 v[178:179], v[178:179], 0, s[66:67]
	s_mov_b32 m0, s6
	ds_read_b128 v[174:177], v182 offset:49152
	ds_read_b128 v[184:187], v182 offset:50176
	ds_read_b128 v[188:191], v182 offset:51200
	ds_read_b128 v[192:195], v182 offset:52224
	ds_read_b128 v[196:199], v182 offset:53248
	ds_read_b128 v[200:203], v182 offset:54272
	ds_read_b128 v[204:207], v182 offset:55296
	ds_read_b128 v[208:211], v182 offset:56320
	global_load_lds_dwordx4 v[178:179], off
	v_lshl_add_u64 v[178:179], v[212:213], 0, s[66:67]
	s_add_i32 m0, s6, 0x2000
	s_add_i32 s6, s43, s14
	global_load_lds_dwordx4 v[178:179], off
	v_lshl_add_u64 v[178:179], v[214:215], 0, s[66:67]
	s_mov_b32 m0, s6
	s_nop 0
	global_load_lds_dwordx4 v[178:179], off
	v_lshl_add_u64 v[178:179], v[216:217], 0, s[66:67]
	s_add_i32 m0, s6, 0x2000
	s_nop 0
	global_load_lds_dwordx4 v[178:179], off
	v_lshl_add_u64 v[178:179], v[218:219], 0, s[66:67]
	s_mov_b32 m0, s61
	s_nop 0
	global_load_lds_dwordx4 v[178:179], off
	v_lshl_add_u64 v[178:179], v[220:221], 0, s[66:67]
	s_mov_b32 m0, s62
	s_nop 0
	global_load_lds_dwordx4 v[178:179], off
	s_waitcnt vmcnt(8)
	s_waitcnt lgkmcnt(0)
	s_barrier
	s_setprio 1
	s_waitcnt lgkmcnt(0)
	v_mfma_f32_16x16x32_bf16 v[76:79], v[52:55], v[174:177], v[76:79]
	v_mfma_f32_16x16x32_bf16 v[80:83], v[68:71], v[174:177], v[80:83]
	v_mfma_f32_16x16x32_bf16 v[60:63], v[52:55], v[188:191], v[60:63]
	v_mfma_f32_16x16x32_bf16 v[64:67], v[68:71], v[188:191], v[64:67]
	v_mfma_f32_16x16x32_bf16 v[24:27], v[52:55], v[196:199], v[24:27]
	v_mfma_f32_16x16x32_bf16 v[28:31], v[68:71], v[196:199], v[28:31]
	v_mfma_f32_16x16x32_bf16 v[8:11], v[52:55], v[204:207], v[8:11]
	v_mfma_f32_16x16x32_bf16 v[12:15], v[68:71], v[204:207], v[12:15]
	v_mfma_f32_16x16x32_bf16 v[76:79], v[56:59], v[184:187], v[76:79]
	v_mfma_f32_16x16x32_bf16 v[80:83], v[72:75], v[184:187], v[80:83]
	v_mfma_f32_16x16x32_bf16 v[60:63], v[56:59], v[192:195], v[60:63]
	v_mfma_f32_16x16x32_bf16 v[64:67], v[72:75], v[192:195], v[64:67]
	v_mfma_f32_16x16x32_bf16 v[24:27], v[56:59], v[200:203], v[24:27]
	v_mfma_f32_16x16x32_bf16 v[28:31], v[72:75], v[200:203], v[28:31]
	v_mfma_f32_16x16x32_bf16 v[8:11], v[56:59], v[208:211], v[8:11]
	v_mfma_f32_16x16x32_bf16 v[12:15], v[72:75], v[208:211], v[12:15]
	s_setprio 0
	s_setprio 1
	v_mfma_f32_16x16x32_bf16 v[44:47], v[158:161], v[174:177], v[44:47]
	v_mfma_f32_16x16x32_bf16 v[68:71], v[162:165], v[184:187], v[44:47]
	v_mfma_f32_16x16x32_bf16 v[44:47], v[166:169], v[174:177], v[48:51]
	v_mfma_f32_16x16x32_bf16 v[36:39], v[158:161], v[188:191], v[36:39]
	v_mfma_f32_16x16x32_bf16 v[40:43], v[166:169], v[188:191], v[40:43]
	v_mfma_f32_16x16x32_bf16 v[16:19], v[158:161], v[196:199], v[16:19]
	v_mfma_f32_16x16x32_bf16 v[20:23], v[166:169], v[196:199], v[20:23]
	v_mfma_f32_16x16x32_bf16 v[0:3], v[158:161], v[204:207], v[0:3]
	v_mfma_f32_16x16x32_bf16 v[4:7], v[166:169], v[204:207], v[4:7]
	v_mfma_f32_16x16x32_bf16 v[72:75], v[170:173], v[184:187], v[44:47]
	v_mfma_f32_16x16x32_bf16 v[36:39], v[162:165], v[192:195], v[36:39]
	v_mfma_f32_16x16x32_bf16 v[40:43], v[170:173], v[192:195], v[40:43]
	v_mfma_f32_16x16x32_bf16 v[16:19], v[162:165], v[200:203], v[16:19]
	v_mfma_f32_16x16x32_bf16 v[20:23], v[170:173], v[200:203], v[20:23]
	v_mfma_f32_16x16x32_bf16 v[0:3], v[162:165], v[208:211], v[0:3]
	v_mfma_f32_16x16x32_bf16 v[4:7], v[170:173], v[208:211], v[4:7]
	s_setprio 0
	s_barrier
	s_add_u32 s4, s4, 0x100
	s_addc_u32 s5, s5, 0
	s_add_u32 s8, s8, 0x100
	s_addc_u32 s9, s9, 0
	s_cmp_ge_i32 s40, s59
	s_mov_b32 s6, s40
	s_cbranch_scc0 .LBB0_380

;     __device__ __forceinline__ void operator()(const f32x4 (&acc)[2][2][4][2], const Unit& u, int wr, int wc, int fr, int fq) const {
;         const int row0 = u.pm * BM + wr * 64 + fr; const int t = u.pn >> 2;
;         bf16_t* base = WM + (t == 1 ? offA : (size_t)0) + (t == 2 ? offG : (size_t)0);
;         const float* bias = t == 0 ? w0 : a0;
;         const int col0 = (u.pn & 3) * BM + wc * 32 + 8 * fq;
;         f32x4 bv[2][2];
; #pragma unroll
;         for (int bj = 0; bj < 2; ++bj)
; #pragma unroll
;             for (int n = 0; n < 2; ++n) bv[bj][n] = (t < 2) ? *(const f32x4*)(bias + col0 + bj * HALF + 4 * n) : (f32x4){0.f, 0.f, 0.f, 0.f};
.LBB0_383:
	s_ashr_i32 s6, s42, 2
	v_readlane_b32 s72, v253, 58
	s_cmp_lt_u32 s42, 4
	v_readlane_b32 s73, v253, 59
	v_readlane_b32 s74, v253, 60
	v_readlane_b32 s75, v253, 61
	v_readlane_b32 s76, v253, 62
	v_readlane_b32 s77, v253, 63
	v_readlane_b32 s78, v255, 0
	v_readlane_b32 s79, v255, 1
	v_readlane_b32 s80, v255, 2
	v_readlane_b32 s81, v255, 3
	v_readlane_b32 s82, v255, 4
	v_readlane_b32 s83, v255, 5
	s_cselect_b64 s[40:41], -1, 0
	v_readlane_b32 s68, v253, 18
	s_and_b64 s[4:5], s[40:41], exec
	v_readlane_b32 s84, v255, 6
	v_readlane_b32 s85, v255, 7
	v_readlane_b32 s70, v253, 20
	v_readlane_b32 s71, v253, 21
	s_cselect_b32 s9, s85, s71
	s_cselect_b32 s8, s84, s70
	s_lshl_b32 s4, s42, 8
	s_and_b32 s4, s4, 0x300
	v_or_b32_e32 v160, s4, v181
	s_cmp_lt_i32 s6, 2
	v_lshlrev_b32_e32 v44, 2, v160
	v_mov_b32_e32 v45, v236
	s_cselect_b64 s[4:5], -1, 0
	s_cmp_gt_i32 s6, 1
	v_lshl_add_u64 v[158:159], s[8:9], 0, v[44:45]
	v_mov_b32_e32 v52, 0
	v_mov_b32_e32 v56, 0
	v_mov_b32_e32 v57, 0
	v_mov_b32_e32 v58, 0
	v_mov_b32_e32 v59, 0
	v_readlane_b32 s86, v255, 8
	v_readlane_b32 s87, v255, 9
	v_readlane_b32 s69, v253, 19
	v_readlane_b32 s72, v253, 22
	v_readlane_b32 s73, v253, 23
	v_readlane_b32 s74, v253, 24
	v_readlane_b32 s75, v253, 25
	v_readlane_b32 s76, v253, 26
	v_readlane_b32 s77, v253, 27
	v_readlane_b32 s78, v253, 28
	v_readlane_b32 s79, v253, 29
	v_readlane_b32 s80, v253, 30
	v_readlane_b32 s81, v253, 31
	v_readlane_b32 s82, v253, 32
	v_readlane_b32 s83, v253, 33
	s_cbranch_scc1 .LBB0_385
	global_load_dwordx4 v[56:59], v[158:159], off

; __device__ __forceinline__ unsigned cvt_pk_bf16(float lo, float hi) { unsigned r; asm volatile("v_cvt_pk_bf16_f32 %0, %1, %2" : "=v"(r) : "v"(lo), "v"(hi)); return r; }
; __device__ __forceinline__ float fast_sigmoid(float x) { return __builtin_amdgcn_rcpf(1.0f + __builtin_amdgcn_exp2f(-x * LOG2E)); }
;     __device__ __forceinline__ void operator()(const f32x4 (&acc)[2][2][4][2], const Unit& u, int wr, int wc, int fr, int fq) const {
;     ...
;             for (int m = 0; m < 4; ++m) {
;                 bf16_t* rowp = base + (size_t)(row0 + ai * HALF + m * 16) * 1024 + col0;
; #pragma unroll
;                 for (int bj = 0; bj < 2; ++bj) {
;                     f32x4 v[2] = {acc[ai][bj][m][0], acc[ai][bj][m][1]};
;                     if (t < 2) {
;                         v[0] += bv[bj][0]; v[1] += bv[bj][1];
; #pragma unroll
;                         for (int n = 0; n < 2; ++n)
; #pragma unroll
;                             for (int j = 0; j < 4; ++j) {
;                                 float x = fast_sigmoid(v[n][j]);
;                                 if (t == 0) x = 1.0f - __builtin_amdgcn_exp2f(x * (-0.6065306597126334f * LOG2E));
;                                 v[n][j] = x;
;                             }
;                     }
;                     u32x4 w; w.x = cvt_pk_bf16(v[0][0], v[0][1]); w.y = cvt_pk_bf16(v[0][2], v[0][3]); w.z = cvt_pk_bf16(v[1][0], v[1][1]); w.w = cvt_pk_bf16(v[1][2], v[1][3]);
;                     *(u32x4*)(rowp + bj * HALF) = w;
.LBB0_393:
	s_cmp_eq_u32 s6, 1
	s_cselect_b32 s4, 0x4000000, 0
	s_cmp_eq_u32 s6, 2
	s_cselect_b32 s5, 0x15000000, 0
	v_lshl_add_u32 v158, s1, 8, v35
	s_add_u32 s1, s19, s4
	s_addc_u32 s6, s58, 0
	s_add_u32 s4, s1, s5
	s_addc_u32 s5, s6, 0
	v_lshlrev_b32_e32 v160, 1, v160
	v_mov_b32_e32 v161, v236
	v_ashrrev_i32_e32 v159, 31, v158
	v_lshl_add_u64 v[160:161], s[4:5], 0, v[160:161]
	v_lshlrev_b64 v[162:163], 11, v[158:159]
	v_lshl_add_u64 v[162:163], v[160:161], 0, v[162:163]
	v_cvt_pk_bf16_f32 v140, v140, v141
	v_cvt_pk_bf16_f32 v141, v142, v143
	v_cvt_pk_bf16_f32 v142, v144, v145
	v_cvt_pk_bf16_f32 v143, v146, v147
	global_store_dwordx4 v[162:163], v[140:143], off
	s_and_b64 vcc, exec, s[42:43]
	s_cbranch_vccnz .LBB0_395
	v_pk_add_f32 v[132:133], v[132:133], v[48:49]
	v_pk_add_f32 v[134:135], v[134:135], v[50:51]
	v_mul_f32_e32 v34, 0xbfb8aa3b, v132
	v_exp_f32_e32 v34, v34
	v_pk_add_f32 v[136:137], v[136:137], v[44:45]
	v_pk_add_f32 v[138:139], v[138:139], v[46:47]
	v_add_f32_e32 v34, 1.0, v34
	v_rcp_f32_e32 v34, v34
	s_nop 0
	v_mul_f32_e32 v132, 0xbf60028a, v34
	v_exp_f32_e32 v132, v132
	s_nop 0
	v_sub_f32_e32 v132, 1.0, v132
	v_cndmask_b32_e64 v132, v34, v132, s[40:41]
	v_mul_f32_e32 v34, 0xbfb8aa3b, v133
	v_exp_f32_e32 v34, v34
	s_nop 0
	v_add_f32_e32 v34, 1.0, v34
	v_rcp_f32_e32 v34, v34
	s_nop 0
	v_mul_f32_e32 v133, 0xbf60028a, v34
	v_exp_f32_e32 v133, v133
	s_nop 0
	v_sub_f32_e32 v133, 1.0, v133
	v_cndmask_b32_e64 v133, v34, v133, s[40:41]
	v_mul_f32_e32 v34, 0xbfb8aa3b, v134
	v_exp_f32_e32 v34, v34
	s_nop 0
	v_add_f32_e32 v34, 1.0, v34
	v_rcp_f32_e32 v34, v34
	s_nop 0
	v_mul_f32_e32 v134, 0xbf60028a, v34
	v_exp_f32_e32 v134, v134
	s_nop 0
	v_sub_f32_e32 v134, 1.0, v134
	v_cndmask_b32_e64 v134, v34, v134, s[40:41]
	v_mul_f32_e32 v34, 0xbfb8aa3b, v135
	v_exp_f32_e32 v34, v34
	s_nop 0
	v_add_f32_e32 v34, 1.0, v34
	v_rcp_f32_e32 v34, v34
	s_nop 0
	v_mul_f32_e32 v135, 0xbf60028a, v34
	v_exp_f32_e32 v135, v135
	s_nop 0
	v_sub_f32_e32 v135, 1.0, v135
	v_cndmask_b32_e64 v135, v34, v135, s[40:41]
	v_mul_f32_e32 v34, 0xbfb8aa3b, v136
	v_exp_f32_e32 v34, v34
	s_nop 0
	v_add_f32_e32 v34, 1.0, v34
	v_rcp_f32_e32 v34, v34
	s_nop 0
	v_mul_f32_e32 v136, 0xbf60028a, v34
	v_exp_f32_e32 v136, v136
	s_nop 0
	v_sub_f32_e32 v136, 1.0, v136
	v_cndmask_b32_e64 v136, v34, v136, s[40:41]
	v_mul_f32_e32 v34, 0xbfb8aa3b, v137
	v_exp_f32_e32 v34, v34
	s_nop 0
	v_add_f32_e32 v34, 1.0, v34
	v_rcp_f32_e32 v34, v34
	s_nop 0
	v_mul_f32_e32 v137, 0xbf60028a, v34
	v_exp_f32_e32 v137, v137
	s_nop 0
	v_sub_f32_e32 v137, 1.0, v137
	v_cndmask_b32_e64 v137, v34, v137, s[40:41]
	v_mul_f32_e32 v34, 0xbfb8aa3b, v138
	v_exp_f32_e32 v34, v34
	s_nop 0
	v_add_f32_e32 v34, 1.0, v34
	v_rcp_f32_e32 v34, v34
	s_nop 0
	v_mul_f32_e32 v138, 0xbf60028a, v34
	v_exp_f32_e32 v138, v138
	s_nop 0
	v_sub_f32_e32 v138, 1.0, v138
	v_cndmask_b32_e64 v138, v34, v138, s[40:41]
	v_mul_f32_e32 v34, 0xbfb8aa3b, v139
	v_exp_f32_e32 v34, v34
	s_nop 0
	v_add_f32_e32 v34, 1.0, v34
	v_rcp_f32_e32 v34, v34
	s_nop 0
	v_mul_f32_e32 v139, 0xbf60028a, v34
	v_exp_f32_e32 v139, v139
	s_nop 0
	v_sub_f32_e32 v139, 1.0, v139
	v_cndmask_b32_e64 v139, v34, v139, s[40:41]
.LBB0_395:
	v_cvt_pk_bf16_f32 v132, v132, v133
	v_cvt_pk_bf16_f32 v133, v134, v135
	v_cvt_pk_bf16_f32 v134, v136, v137
	v_cvt_pk_bf16_f32 v135, v138, v139
	global_store_dwordx4 v[162:163], v[132:135], off offset:256
	s_and_b64 vcc, exec, s[42:43]
	s_cbranch_vccnz .LBB0_397
	v_pk_add_f32 v[124:125], v[124:125], v[56:57]
	v_pk_add_f32 v[126:127], v[126:127], v[58:59]
	v_mul_f32_e32 v34, 0xbfb8aa3b, v124
	v_exp_f32_e32 v34, v34
	v_pk_add_f32 v[128:129], v[128:129], v[52:53]
	v_pk_add_f32 v[130:131], v[130:131], v[54:55]
	v_add_f32_e32 v34, 1.0, v34
	v_rcp_f32_e32 v34, v34
	s_nop 0
	v_mul_f32_e32 v124, 0xbf60028a, v34
	v_exp_f32_e32 v124, v124
	s_nop 0
	v_sub_f32_e32 v124, 1.0, v124
	v_cndmask_b32_e64 v124, v34, v124, s[40:41]
	v_mul_f32_e32 v34, 0xbfb8aa3b, v125
	v_exp_f32_e32 v34, v34
	s_nop 0
	v_add_f32_e32 v34, 1.0, v34
	v_rcp_f32_e32 v34, v34
	s_nop 0
	v_mul_f32_e32 v125, 0xbf60028a, v34
	v_exp_f32_e32 v125, v125
	s_nop 0
	v_sub_f32_e32 v125, 1.0, v125
	v_cndmask_b32_e64 v125, v34, v125, s[40:41]
	v_mul_f32_e32 v34, 0xbfb8aa3b, v126
	v_exp_f32_e32 v34, v34
	s_nop 0
	v_add_f32_e32 v34, 1.0, v34
	v_rcp_f32_e32 v34, v34
	s_nop 0
	v_mul_f32_e32 v126, 0xbf60028a, v34
	v_exp_f32_e32 v126, v126
	s_nop 0
	v_sub_f32_e32 v126, 1.0, v126
	v_cndmask_b32_e64 v126, v34, v126, s[40:41]
	v_mul_f32_e32 v34, 0xbfb8aa3b, v127
	v_exp_f32_e32 v34, v34
	s_nop 0
	v_add_f32_e32 v34, 1.0, v34
	v_rcp_f32_e32 v34, v34
	s_nop 0
	v_mul_f32_e32 v127, 0xbf60028a, v34
	v_exp_f32_e32 v127, v127
	s_nop 0
	v_sub_f32_e32 v127, 1.0, v127
	v_cndmask_b32_e64 v127, v34, v127, s[40:41]
	v_mul_f32_e32 v34, 0xbfb8aa3b, v128
	v_exp_f32_e32 v34, v34
	s_nop 0
	v_add_f32_e32 v34, 1.0, v34
	v_rcp_f32_e32 v34, v34
	s_nop 0
	v_mul_f32_e32 v128, 0xbf60028a, v34
	v_exp_f32_e32 v128, v128
	s_nop 0
	v_sub_f32_e32 v128, 1.0, v128
	v_cndmask_b32_e64 v128, v34, v128, s[40:41]
	v_mul_f32_e32 v34, 0xbfb8aa3b, v129
	v_exp_f32_e32 v34, v34
	s_nop 0
	v_add_f32_e32 v34, 1.0, v34
	v_rcp_f32_e32 v34, v34
	s_nop 0
	v_mul_f32_e32 v129, 0xbf60028a, v34
	v_exp_f32_e32 v129, v129
	s_nop 0
	v_sub_f32_e32 v129, 1.0, v129
	v_cndmask_b32_e64 v129, v34, v129, s[40:41]
	v_mul_f32_e32 v34, 0xbfb8aa3b, v130
	v_exp_f32_e32 v34, v34
	s_nop 0
	v_add_f32_e32 v34, 1.0, v34
	v_rcp_f32_e32 v34, v34
	s_nop 0
	v_mul_f32_e32 v130, 0xbf60028a, v34
	v_exp_f32_e32 v130, v130
	s_nop 0
	v_sub_f32_e32 v130, 1.0, v130
	v_cndmask_b32_e64 v130, v34, v130, s[40:41]
	v_mul_f32_e32 v34, 0xbfb8aa3b, v131
	v_exp_f32_e32 v34, v34
	s_nop 0
	v_add_f32_e32 v34, 1.0, v34
	v_rcp_f32_e32 v34, v34
	s_nop 0
	v_mul_f32_e32 v131, 0xbf60028a, v34
	v_exp_f32_e32 v131, v131
	s_nop 0
	v_sub_f32_e32 v131, 1.0, v131
	v_cndmask_b32_e64 v131, v34, v131, s[40:41]
; __device__ __forceinline__ unsigned cvt_pk_bf16(float lo, float hi) { unsigned r; asm volatile("v_cvt_pk_bf16_f32 %0, %1, %2" : "=v"(r) : "v"(lo), "v"(hi)); return r; }
; __device__ __forceinline__ float fast_sigmoid(float x) { return __builtin_amdgcn_rcpf(1.0f + __builtin_amdgcn_exp2f(-x * LOG2E)); }
;     __device__ __forceinline__ void operator()(const f32x4 (&acc)[2][2][4][2], const Unit& u, int wr, int wc, int fr, int fq) const {
;     ...
;             for (int m = 0; m < 4; ++m) {
;                 bf16_t* rowp = base + (size_t)(row0 + ai * HALF + m * 16) * 1024 + col0;
; #pragma unroll
;                 for (int bj = 0; bj < 2; ++bj) {
;                     f32x4 v[2] = {acc[ai][bj][m][0], acc[ai][bj][m][1]};
;                     if (t < 2) {
;                         v[0] += bv[bj][0]; v[1] += bv[bj][1];
; #pragma unroll
;                         for (int n = 0; n < 2; ++n)
; #pragma unroll
;                             for (int j = 0; j < 4; ++j) {
;                                 float x = fast_sigmoid(v[n][j]);
;                                 if (t == 0) x = 1.0f - __builtin_amdgcn_exp2f(x * (-0.6065306597126334f * LOG2E));
;                                 v[n][j] = x;
;                             }
;                     }
;                     u32x4 w; w.x = cvt_pk_bf16(v[0][0], v[0][1]); w.y = cvt_pk_bf16(v[0][2], v[0][3]); w.z = cvt_pk_bf16(v[1][0], v[1][1]); w.w = cvt_pk_bf16(v[1][2], v[1][3]);
;                     *(u32x4*)(rowp + bj * HALF) = w;
.LBB0_397:
	v_or_b32_e32 v132, 16, v158
	v_ashrrev_i32_e32 v133, 31, v132
	v_lshlrev_b64 v[132:133], 11, v[132:133]
	v_lshl_add_u64 v[132:133], v[160:161], 0, v[132:133]
	v_cvt_pk_bf16_f32 v124, v124, v125
	v_cvt_pk_bf16_f32 v125, v126, v127
	v_cvt_pk_bf16_f32 v126, v128, v129
	v_cvt_pk_bf16_f32 v127, v130, v131
	global_store_dwordx4 v[132:133], v[124:127], off
	s_and_b64 vcc, exec, s[42:43]
	s_cbranch_vccnz .LBB0_399
	v_pk_add_f32 v[116:117], v[116:117], v[48:49]
	v_pk_add_f32 v[118:119], v[118:119], v[50:51]
	v_mul_f32_e32 v34, 0xbfb8aa3b, v116
	v_exp_f32_e32 v34, v34
	v_pk_add_f32 v[120:121], v[120:121], v[44:45]
	v_pk_add_f32 v[122:123], v[122:123], v[46:47]
	v_add_f32_e32 v34, 1.0, v34
	v_rcp_f32_e32 v34, v34
	s_nop 0
	v_mul_f32_e32 v116, 0xbf60028a, v34
	v_exp_f32_e32 v116, v116
	s_nop 0
	v_sub_f32_e32 v116, 1.0, v116
	v_cndmask_b32_e64 v116, v34, v116, s[40:41]
	v_mul_f32_e32 v34, 0xbfb8aa3b, v117
	v_exp_f32_e32 v34, v34
	s_nop 0
	v_add_f32_e32 v34, 1.0, v34
	v_rcp_f32_e32 v34, v34
	s_nop 0
	v_mul_f32_e32 v117, 0xbf60028a, v34
	v_exp_f32_e32 v117, v117
	s_nop 0
	v_sub_f32_e32 v117, 1.0, v117
	v_cndmask_b32_e64 v117, v34, v117, s[40:41]
	v_mul_f32_e32 v34, 0xbfb8aa3b, v118
	v_exp_f32_e32 v34, v34
	s_nop 0
	v_add_f32_e32 v34, 1.0, v34
	v_rcp_f32_e32 v34, v34
	s_nop 0
	v_mul_f32_e32 v118, 0xbf60028a, v34
	v_exp_f32_e32 v118, v118
	s_nop 0
	v_sub_f32_e32 v118, 1.0, v118
	v_cndmask_b32_e64 v118, v34, v118, s[40:41]
	v_mul_f32_e32 v34, 0xbfb8aa3b, v119
	v_exp_f32_e32 v34, v34
	s_nop 0
	v_add_f32_e32 v34, 1.0, v34
	v_rcp_f32_e32 v34, v34
	s_nop 0
	v_mul_f32_e32 v119, 0xbf60028a, v34
	v_exp_f32_e32 v119, v119
	s_nop 0
	v_sub_f32_e32 v119, 1.0, v119
	v_cndmask_b32_e64 v119, v34, v119, s[40:41]
	v_mul_f32_e32 v34, 0xbfb8aa3b, v120
	v_exp_f32_e32 v34, v34
	s_nop 0
	v_add_f32_e32 v34, 1.0, v34
	v_rcp_f32_e32 v34, v34
	s_nop 0
	v_mul_f32_e32 v120, 0xbf60028a, v34
	v_exp_f32_e32 v120, v120
	s_nop 0
	v_sub_f32_e32 v120, 1.0, v120
	v_cndmask_b32_e64 v120, v34, v120, s[40:41]
	v_mul_f32_e32 v34, 0xbfb8aa3b, v121
	v_exp_f32_e32 v34, v34
	s_nop 0
	v_add_f32_e32 v34, 1.0, v34
	v_rcp_f32_e32 v34, v34
	s_nop 0
	v_mul_f32_e32 v121, 0xbf60028a, v34
	v_exp_f32_e32 v121, v121
	s_nop 0
	v_sub_f32_e32 v121, 1.0, v121
	v_cndmask_b32_e64 v121, v34, v121, s[40:41]
	v_mul_f32_e32 v34, 0xbfb8aa3b, v122
	v_exp_f32_e32 v34, v34
	s_nop 0
	v_add_f32_e32 v34, 1.0, v34
	v_rcp_f32_e32 v34, v34
	s_nop 0
	v_mul_f32_e32 v122, 0xbf60028a, v34
	v_exp_f32_e32 v122, v122
	s_nop 0
	v_sub_f32_e32 v122, 1.0, v122
	v_cndmask_b32_e64 v122, v34, v122, s[40:41]
	v_mul_f32_e32 v34, 0xbfb8aa3b, v123
	v_exp_f32_e32 v34, v34
	s_nop 0
	v_add_f32_e32 v34, 1.0, v34
	v_rcp_f32_e32 v34, v34
	s_nop 0
	v_mul_f32_e32 v123, 0xbf60028a, v34
	v_exp_f32_e32 v123, v123
	s_nop 0
	v_sub_f32_e32 v123, 1.0, v123
	v_cndmask_b32_e64 v123, v34, v123, s[40:41]
.LBB0_399:
	v_cvt_pk_bf16_f32 v116, v116, v117
	v_cvt_pk_bf16_f32 v117, v118, v119
	v_cvt_pk_bf16_f32 v118, v120, v121
	v_cvt_pk_bf16_f32 v119, v122, v123
	global_store_dwordx4 v[132:133], v[116:119], off offset:256
	s_and_b64 vcc, exec, s[42:43]
	s_cbranch_vccnz .LBB0_401
	v_pk_add_f32 v[108:109], v[108:109], v[56:57]
	v_pk_add_f32 v[110:111], v[110:111], v[58:59]
	v_mul_f32_e32 v34, 0xbfb8aa3b, v108
	v_exp_f32_e32 v34, v34
	v_pk_add_f32 v[112:113], v[112:113], v[52:53]
	v_pk_add_f32 v[114:115], v[114:115], v[54:55]
	v_add_f32_e32 v34, 1.0, v34
	v_rcp_f32_e32 v34, v34
	s_nop 0
	v_mul_f32_e32 v108, 0xbf60028a, v34
	v_exp_f32_e32 v108, v108
	s_nop 0
	v_sub_f32_e32 v108, 1.0, v108
	v_cndmask_b32_e64 v108, v34, v108, s[40:41]
	v_mul_f32_e32 v34, 0xbfb8aa3b, v109
	v_exp_f32_e32 v34, v34
	s_nop 0
	v_add_f32_e32 v34, 1.0, v34
	v_rcp_f32_e32 v34, v34
	s_nop 0
	v_mul_f32_e32 v109, 0xbf60028a, v34
	v_exp_f32_e32 v109, v109
	s_nop 0
	v_sub_f32_e32 v109, 1.0, v109
	v_cndmask_b32_e64 v109, v34, v109, s[40:41]
	v_mul_f32_e32 v34, 0xbfb8aa3b, v110
	v_exp_f32_e32 v34, v34
	s_nop 0
	v_add_f32_e32 v34, 1.0, v34
	v_rcp_f32_e32 v34, v34
	s_nop 0
	v_mul_f32_e32 v110, 0xbf60028a, v34
	v_exp_f32_e32 v110, v110
	s_nop 0
	v_sub_f32_e32 v110, 1.0, v110
	v_cndmask_b32_e64 v110, v34, v110, s[40:41]
	v_mul_f32_e32 v34, 0xbfb8aa3b, v111
	v_exp_f32_e32 v34, v34
	s_nop 0
	v_add_f32_e32 v34, 1.0, v34
	v_rcp_f32_e32 v34, v34
	s_nop 0
	v_mul_f32_e32 v111, 0xbf60028a, v34
	v_exp_f32_e32 v111, v111
	s_nop 0
	v_sub_f32_e32 v111, 1.0, v111
	v_cndmask_b32_e64 v111, v34, v111, s[40:41]
	v_mul_f32_e32 v34, 0xbfb8aa3b, v112
	v_exp_f32_e32 v34, v34
	s_nop 0
	v_add_f32_e32 v34, 1.0, v34
	v_rcp_f32_e32 v34, v34
	s_nop 0
	v_mul_f32_e32 v112, 0xbf60028a, v34
	v_exp_f32_e32 v112, v112
	s_nop 0
	v_sub_f32_e32 v112, 1.0, v112
	v_cndmask_b32_e64 v112, v34, v112, s[40:41]
	v_mul_f32_e32 v34, 0xbfb8aa3b, v113
	v_exp_f32_e32 v34, v34
	s_nop 0
	v_add_f32_e32 v34, 1.0, v34
	v_rcp_f32_e32 v34, v34
	s_nop 0
	v_mul_f32_e32 v113, 0xbf60028a, v34
	v_exp_f32_e32 v113, v113
	s_nop 0
	v_sub_f32_e32 v113, 1.0, v113
	v_cndmask_b32_e64 v113, v34, v113, s[40:41]
	v_mul_f32_e32 v34, 0xbfb8aa3b, v114
	v_exp_f32_e32 v34, v34
	s_nop 0
	v_add_f32_e32 v34, 1.0, v34
	v_rcp_f32_e32 v34, v34
	s_nop 0
	v_mul_f32_e32 v114, 0xbf60028a, v34
	v_exp_f32_e32 v114, v114
	s_nop 0
	v_sub_f32_e32 v114, 1.0, v114
	v_cndmask_b32_e64 v114, v34, v114, s[40:41]
	v_mul_f32_e32 v34, 0xbfb8aa3b, v115
	v_exp_f32_e32 v34, v34
	s_nop 0
	v_add_f32_e32 v34, 1.0, v34
	v_rcp_f32_e32 v34, v34
	s_nop 0
	v_mul_f32_e32 v115, 0xbf60028a, v34
	v_exp_f32_e32 v115, v115
	s_nop 0
	v_sub_f32_e32 v115, 1.0, v115
	v_cndmask_b32_e64 v115, v34, v115, s[40:41]
; __device__ __forceinline__ unsigned cvt_pk_bf16(float lo, float hi) { unsigned r; asm volatile("v_cvt_pk_bf16_f32 %0, %1, %2" : "=v"(r) : "v"(lo), "v"(hi)); return r; }
; __device__ __forceinline__ float fast_sigmoid(float x) { return __builtin_amdgcn_rcpf(1.0f + __builtin_amdgcn_exp2f(-x * LOG2E)); }
;     __device__ __forceinline__ void operator()(const f32x4 (&acc)[2][2][4][2], const Unit& u, int wr, int wc, int fr, int fq) const {
;     ...
;             for (int m = 0; m < 4; ++m) {
;                 bf16_t* rowp = base + (size_t)(row0 + ai * HALF + m * 16) * 1024 + col0;
; #pragma unroll
;                 for (int bj = 0; bj < 2; ++bj) {
;                     f32x4 v[2] = {acc[ai][bj][m][0], acc[ai][bj][m][1]};
;                     if (t < 2) {
;                         v[0] += bv[bj][0]; v[1] += bv[bj][1];
; #pragma unroll
;                         for (int n = 0; n < 2; ++n)
; #pragma unroll
;                             for (int j = 0; j < 4; ++j) {
;                                 float x = fast_sigmoid(v[n][j]);
;                                 if (t == 0) x = 1.0f - __builtin_amdgcn_exp2f(x * (-0.6065306597126334f * LOG2E));
;                                 v[n][j] = x;
;                             }
;                     }
;                     u32x4 w; w.x = cvt_pk_bf16(v[0][0], v[0][1]); w.y = cvt_pk_bf16(v[0][2], v[0][3]); w.z = cvt_pk_bf16(v[1][0], v[1][1]); w.w = cvt_pk_bf16(v[1][2], v[1][3]);
;                     *(u32x4*)(rowp + bj * HALF) = w;
.LBB0_401:
	v_or_b32_e32 v116, 32, v158
	v_ashrrev_i32_e32 v117, 31, v116
	v_lshlrev_b64 v[116:117], 11, v[116:117]
	v_lshl_add_u64 v[116:117], v[160:161], 0, v[116:117]
	v_cvt_pk_bf16_f32 v108, v108, v109
	v_cvt_pk_bf16_f32 v109, v110, v111
	v_cvt_pk_bf16_f32 v110, v112, v113
	v_cvt_pk_bf16_f32 v111, v114, v115
	global_store_dwordx4 v[116:117], v[108:111], off
	s_and_b64 vcc, exec, s[42:43]
	s_cbranch_vccnz .LBB0_403
	v_pk_add_f32 v[100:101], v[100:101], v[48:49]
	v_pk_add_f32 v[102:103], v[102:103], v[50:51]
	v_mul_f32_e32 v34, 0xbfb8aa3b, v100
	v_exp_f32_e32 v34, v34
	v_pk_add_f32 v[104:105], v[104:105], v[44:45]
	v_pk_add_f32 v[106:107], v[106:107], v[46:47]
	v_add_f32_e32 v34, 1.0, v34
	v_rcp_f32_e32 v34, v34
	s_nop 0
	v_mul_f32_e32 v100, 0xbf60028a, v34
	v_exp_f32_e32 v100, v100
	s_nop 0
	v_sub_f32_e32 v100, 1.0, v100
	v_cndmask_b32_e64 v100, v34, v100, s[40:41]
	v_mul_f32_e32 v34, 0xbfb8aa3b, v101
	v_exp_f32_e32 v34, v34
	s_nop 0
	v_add_f32_e32 v34, 1.0, v34
	v_rcp_f32_e32 v34, v34
	s_nop 0
	v_mul_f32_e32 v101, 0xbf60028a, v34
	v_exp_f32_e32 v101, v101
	s_nop 0
	v_sub_f32_e32 v101, 1.0, v101
	v_cndmask_b32_e64 v101, v34, v101, s[40:41]
	v_mul_f32_e32 v34, 0xbfb8aa3b, v102
	v_exp_f32_e32 v34, v34
	s_nop 0
	v_add_f32_e32 v34, 1.0, v34
	v_rcp_f32_e32 v34, v34
	s_nop 0
	v_mul_f32_e32 v102, 0xbf60028a, v34
	v_exp_f32_e32 v102, v102
	s_nop 0
	v_sub_f32_e32 v102, 1.0, v102
	v_cndmask_b32_e64 v102, v34, v102, s[40:41]
	v_mul_f32_e32 v34, 0xbfb8aa3b, v103
	v_exp_f32_e32 v34, v34
	s_nop 0
	v_add_f32_e32 v34, 1.0, v34
	v_rcp_f32_e32 v34, v34
	s_nop 0
	v_mul_f32_e32 v103, 0xbf60028a, v34
	v_exp_f32_e32 v103, v103
	s_nop 0
	v_sub_f32_e32 v103, 1.0, v103
	v_cndmask_b32_e64 v103, v34, v103, s[40:41]
	v_mul_f32_e32 v34, 0xbfb8aa3b, v104
	v_exp_f32_e32 v34, v34
	s_nop 0
	v_add_f32_e32 v34, 1.0, v34
	v_rcp_f32_e32 v34, v34
	s_nop 0
	v_mul_f32_e32 v104, 0xbf60028a, v34
	v_exp_f32_e32 v104, v104
	s_nop 0
	v_sub_f32_e32 v104, 1.0, v104
	v_cndmask_b32_e64 v104, v34, v104, s[40:41]
	v_mul_f32_e32 v34, 0xbfb8aa3b, v105
	v_exp_f32_e32 v34, v34
	s_nop 0
	v_add_f32_e32 v34, 1.0, v34
	v_rcp_f32_e32 v34, v34
	s_nop 0
	v_mul_f32_e32 v105, 0xbf60028a, v34
	v_exp_f32_e32 v105, v105
	s_nop 0
	v_sub_f32_e32 v105, 1.0, v105
	v_cndmask_b32_e64 v105, v34, v105, s[40:41]
	v_mul_f32_e32 v34, 0xbfb8aa3b, v106
	v_exp_f32_e32 v34, v34
	s_nop 0
	v_add_f32_e32 v34, 1.0, v34
	v_rcp_f32_e32 v34, v34
	s_nop 0
	v_mul_f32_e32 v106, 0xbf60028a, v34
	v_exp_f32_e32 v106, v106
	s_nop 0
	v_sub_f32_e32 v106, 1.0, v106
	v_cndmask_b32_e64 v106, v34, v106, s[40:41]
	v_mul_f32_e32 v34, 0xbfb8aa3b, v107
	v_exp_f32_e32 v34, v34
	s_nop 0
	v_add_f32_e32 v34, 1.0, v34
	v_rcp_f32_e32 v34, v34
	s_nop 0
	v_mul_f32_e32 v107, 0xbf60028a, v34
	v_exp_f32_e32 v107, v107
	s_nop 0
	v_sub_f32_e32 v107, 1.0, v107
	v_cndmask_b32_e64 v107, v34, v107, s[40:41]
.LBB0_403:
	v_cvt_pk_bf16_f32 v100, v100, v101
	v_cvt_pk_bf16_f32 v101, v102, v103
	v_cvt_pk_bf16_f32 v102, v104, v105
	v_cvt_pk_bf16_f32 v103, v106, v107
	global_store_dwordx4 v[116:117], v[100:103], off offset:256
	s_and_b64 vcc, exec, s[42:43]
	s_cbranch_vccnz .LBB0_405
	v_pk_add_f32 v[92:93], v[92:93], v[56:57]
	v_pk_add_f32 v[94:95], v[94:95], v[58:59]
	v_mul_f32_e32 v34, 0xbfb8aa3b, v92
	v_exp_f32_e32 v34, v34
	v_pk_add_f32 v[96:97], v[96:97], v[52:53]
	v_pk_add_f32 v[98:99], v[98:99], v[54:55]
	v_add_f32_e32 v34, 1.0, v34
	v_rcp_f32_e32 v34, v34
	s_nop 0
	v_mul_f32_e32 v92, 0xbf60028a, v34
	v_exp_f32_e32 v92, v92
	s_nop 0
	v_sub_f32_e32 v92, 1.0, v92
	v_cndmask_b32_e64 v92, v34, v92, s[40:41]
	v_mul_f32_e32 v34, 0xbfb8aa3b, v93
	v_exp_f32_e32 v34, v34
	s_nop 0
	v_add_f32_e32 v34, 1.0, v34
	v_rcp_f32_e32 v34, v34
	s_nop 0
	v_mul_f32_e32 v93, 0xbf60028a, v34
	v_exp_f32_e32 v93, v93
	s_nop 0
	v_sub_f32_e32 v93, 1.0, v93
	v_cndmask_b32_e64 v93, v34, v93, s[40:41]
	v_mul_f32_e32 v34, 0xbfb8aa3b, v94
	v_exp_f32_e32 v34, v34
	s_nop 0
	v_add_f32_e32 v34, 1.0, v34
	v_rcp_f32_e32 v34, v34
	s_nop 0
	v_mul_f32_e32 v94, 0xbf60028a, v34
	v_exp_f32_e32 v94, v94
	s_nop 0
	v_sub_f32_e32 v94, 1.0, v94
	v_cndmask_b32_e64 v94, v34, v94, s[40:41]
	v_mul_f32_e32 v34, 0xbfb8aa3b, v95
	v_exp_f32_e32 v34, v34
	s_nop 0
	v_add_f32_e32 v34, 1.0, v34
	v_rcp_f32_e32 v34, v34
	s_nop 0
	v_mul_f32_e32 v95, 0xbf60028a, v34
	v_exp_f32_e32 v95, v95
	s_nop 0
	v_sub_f32_e32 v95, 1.0, v95
	v_cndmask_b32_e64 v95, v34, v95, s[40:41]
	v_mul_f32_e32 v34, 0xbfb8aa3b, v96
	v_exp_f32_e32 v34, v34
	s_nop 0
	v_add_f32_e32 v34, 1.0, v34
	v_rcp_f32_e32 v34, v34
	s_nop 0
	v_mul_f32_e32 v96, 0xbf60028a, v34
	v_exp_f32_e32 v96, v96
	s_nop 0
	v_sub_f32_e32 v96, 1.0, v96
	v_cndmask_b32_e64 v96, v34, v96, s[40:41]
	v_mul_f32_e32 v34, 0xbfb8aa3b, v97
	v_exp_f32_e32 v34, v34
	s_nop 0
	v_add_f32_e32 v34, 1.0, v34
	v_rcp_f32_e32 v34, v34
	s_nop 0
	v_mul_f32_e32 v97, 0xbf60028a, v34
	v_exp_f32_e32 v97, v97
	s_nop 0
	v_sub_f32_e32 v97, 1.0, v97
	v_cndmask_b32_e64 v97, v34, v97, s[40:41]
	v_mul_f32_e32 v34, 0xbfb8aa3b, v98
	v_exp_f32_e32 v34, v34
	s_nop 0
	v_add_f32_e32 v34, 1.0, v34
	v_rcp_f32_e32 v34, v34
	s_nop 0
	v_mul_f32_e32 v98, 0xbf60028a, v34
	v_exp_f32_e32 v98, v98
	s_nop 0
	v_sub_f32_e32 v98, 1.0, v98
	v_cndmask_b32_e64 v98, v34, v98, s[40:41]
	v_mul_f32_e32 v34, 0xbfb8aa3b, v99
	v_exp_f32_e32 v34, v34
	s_nop 0
	v_add_f32_e32 v34, 1.0, v34
	v_rcp_f32_e32 v34, v34
	s_nop 0
	v_mul_f32_e32 v99, 0xbf60028a, v34
	v_exp_f32_e32 v99, v99
	s_nop 0
	v_sub_f32_e32 v99, 1.0, v99
	v_cndmask_b32_e64 v99, v34, v99, s[40:41]
; __device__ __forceinline__ unsigned cvt_pk_bf16(float lo, float hi) { unsigned r; asm volatile("v_cvt_pk_bf16_f32 %0, %1, %2" : "=v"(r) : "v"(lo), "v"(hi)); return r; }
; __device__ __forceinline__ float fast_sigmoid(float x) { return __builtin_amdgcn_rcpf(1.0f + __builtin_amdgcn_exp2f(-x * LOG2E)); }
;     __device__ __forceinline__ void operator()(const f32x4 (&acc)[2][2][4][2], const Unit& u, int wr, int wc, int fr, int fq) const {
;     ...
;             for (int m = 0; m < 4; ++m) {
;                 bf16_t* rowp = base + (size_t)(row0 + ai * HALF + m * 16) * 1024 + col0;
; #pragma unroll
;                 for (int bj = 0; bj < 2; ++bj) {
;                     f32x4 v[2] = {acc[ai][bj][m][0], acc[ai][bj][m][1]};
;                     if (t < 2) {
;                         v[0] += bv[bj][0]; v[1] += bv[bj][1];
; #pragma unroll
;                         for (int n = 0; n < 2; ++n)
; #pragma unroll
;                             for (int j = 0; j < 4; ++j) {
;                                 float x = fast_sigmoid(v[n][j]);
;                                 if (t == 0) x = 1.0f - __builtin_amdgcn_exp2f(x * (-0.6065306597126334f * LOG2E));
;                                 v[n][j] = x;
;                             }
;                     }
;                     u32x4 w; w.x = cvt_pk_bf16(v[0][0], v[0][1]); w.y = cvt_pk_bf16(v[0][2], v[0][3]); w.z = cvt_pk_bf16(v[1][0], v[1][1]); w.w = cvt_pk_bf16(v[1][2], v[1][3]);
;                     *(u32x4*)(rowp + bj * HALF) = w;
.LBB0_405:
	v_or_b32_e32 v100, 48, v158
	v_ashrrev_i32_e32 v101, 31, v100
	v_lshlrev_b64 v[100:101], 11, v[100:101]
	v_lshl_add_u64 v[100:101], v[160:161], 0, v[100:101]
	v_cvt_pk_bf16_f32 v92, v92, v93
	v_cvt_pk_bf16_f32 v93, v94, v95
	v_cvt_pk_bf16_f32 v94, v96, v97
	v_cvt_pk_bf16_f32 v95, v98, v99
	global_store_dwordx4 v[100:101], v[92:95], off
	s_and_b64 vcc, exec, s[42:43]
	s_cbranch_vccnz .LBB0_407
	v_pk_add_f32 v[84:85], v[84:85], v[48:49]
	v_pk_add_f32 v[86:87], v[86:87], v[50:51]
	v_mul_f32_e32 v34, 0xbfb8aa3b, v84
	v_exp_f32_e32 v34, v34
	v_pk_add_f32 v[88:89], v[88:89], v[44:45]
	v_pk_add_f32 v[90:91], v[90:91], v[46:47]
	v_add_f32_e32 v34, 1.0, v34
	v_rcp_f32_e32 v34, v34
	s_nop 0
	v_mul_f32_e32 v84, 0xbf60028a, v34
	v_exp_f32_e32 v84, v84
	s_nop 0
	v_sub_f32_e32 v84, 1.0, v84
	v_cndmask_b32_e64 v84, v34, v84, s[40:41]
	v_mul_f32_e32 v34, 0xbfb8aa3b, v85
	v_exp_f32_e32 v34, v34
	s_nop 0
	v_add_f32_e32 v34, 1.0, v34
	v_rcp_f32_e32 v34, v34
	s_nop 0
	v_mul_f32_e32 v85, 0xbf60028a, v34
	v_exp_f32_e32 v85, v85
	s_nop 0
	v_sub_f32_e32 v85, 1.0, v85
	v_cndmask_b32_e64 v85, v34, v85, s[40:41]
	v_mul_f32_e32 v34, 0xbfb8aa3b, v86
	v_exp_f32_e32 v34, v34
	s_nop 0
	v_add_f32_e32 v34, 1.0, v34
	v_rcp_f32_e32 v34, v34
	s_nop 0
	v_mul_f32_e32 v86, 0xbf60028a, v34
	v_exp_f32_e32 v86, v86
	s_nop 0
	v_sub_f32_e32 v86, 1.0, v86
	v_cndmask_b32_e64 v86, v34, v86, s[40:41]
	v_mul_f32_e32 v34, 0xbfb8aa3b, v87
	v_exp_f32_e32 v34, v34
	s_nop 0
	v_add_f32_e32 v34, 1.0, v34
	v_rcp_f32_e32 v34, v34
	s_nop 0
	v_mul_f32_e32 v87, 0xbf60028a, v34
	v_exp_f32_e32 v87, v87
	s_nop 0
	v_sub_f32_e32 v87, 1.0, v87
	v_cndmask_b32_e64 v87, v34, v87, s[40:41]
	v_mul_f32_e32 v34, 0xbfb8aa3b, v88
	v_exp_f32_e32 v34, v34
	s_nop 0
	v_add_f32_e32 v34, 1.0, v34
	v_rcp_f32_e32 v34, v34
	s_nop 0
	v_mul_f32_e32 v88, 0xbf60028a, v34
	v_exp_f32_e32 v88, v88
	s_nop 0
	v_sub_f32_e32 v88, 1.0, v88
	v_cndmask_b32_e64 v88, v34, v88, s[40:41]
	v_mul_f32_e32 v34, 0xbfb8aa3b, v89
	v_exp_f32_e32 v34, v34
	s_nop 0
	v_add_f32_e32 v34, 1.0, v34
	v_rcp_f32_e32 v34, v34
	s_nop 0
	v_mul_f32_e32 v89, 0xbf60028a, v34
	v_exp_f32_e32 v89, v89
	s_nop 0
	v_sub_f32_e32 v89, 1.0, v89
	v_cndmask_b32_e64 v89, v34, v89, s[40:41]
	v_mul_f32_e32 v34, 0xbfb8aa3b, v90
	v_exp_f32_e32 v34, v34
	s_nop 0
	v_add_f32_e32 v34, 1.0, v34
	v_rcp_f32_e32 v34, v34
	s_nop 0
	v_mul_f32_e32 v90, 0xbf60028a, v34
	v_exp_f32_e32 v90, v90
	s_nop 0
	v_sub_f32_e32 v90, 1.0, v90
	v_cndmask_b32_e64 v90, v34, v90, s[40:41]
	v_mul_f32_e32 v34, 0xbfb8aa3b, v91
	v_exp_f32_e32 v34, v34
	s_nop 0
	v_add_f32_e32 v34, 1.0, v34
	v_rcp_f32_e32 v34, v34
	s_nop 0
	v_mul_f32_e32 v91, 0xbf60028a, v34
	v_exp_f32_e32 v91, v91
	s_nop 0
	v_sub_f32_e32 v91, 1.0, v91
	v_cndmask_b32_e64 v91, v34, v91, s[40:41]
.LBB0_407:
	v_cvt_pk_bf16_f32 v84, v84, v85
	v_cvt_pk_bf16_f32 v85, v86, v87
	v_cvt_pk_bf16_f32 v86, v88, v89
	v_cvt_pk_bf16_f32 v87, v90, v91
	global_store_dwordx4 v[100:101], v[84:87], off offset:256
	s_and_b64 vcc, exec, s[42:43]
	s_cbranch_vccnz .LBB0_409
	v_pk_add_f32 v[76:77], v[76:77], v[56:57]
	v_pk_add_f32 v[78:79], v[78:79], v[58:59]
	v_mul_f32_e32 v34, 0xbfb8aa3b, v76
	v_exp_f32_e32 v34, v34
	v_pk_add_f32 v[80:81], v[80:81], v[52:53]
	v_pk_add_f32 v[82:83], v[82:83], v[54:55]
	v_add_f32_e32 v34, 1.0, v34
	v_rcp_f32_e32 v34, v34
	s_nop 0
	v_mul_f32_e32 v76, 0xbf60028a, v34
	v_exp_f32_e32 v76, v76
	s_nop 0
	v_sub_f32_e32 v76, 1.0, v76
	v_cndmask_b32_e64 v76, v34, v76, s[40:41]
	v_mul_f32_e32 v34, 0xbfb8aa3b, v77
	v_exp_f32_e32 v34, v34
	s_nop 0
	v_add_f32_e32 v34, 1.0, v34
	v_rcp_f32_e32 v34, v34
	s_nop 0
	v_mul_f32_e32 v77, 0xbf60028a, v34
	v_exp_f32_e32 v77, v77
	s_nop 0
	v_sub_f32_e32 v77, 1.0, v77
	v_cndmask_b32_e64 v77, v34, v77, s[40:41]
	v_mul_f32_e32 v34, 0xbfb8aa3b, v78
	v_exp_f32_e32 v34, v34
	s_nop 0
	v_add_f32_e32 v34, 1.0, v34
	v_rcp_f32_e32 v34, v34
	s_nop 0
	v_mul_f32_e32 v78, 0xbf60028a, v34
	v_exp_f32_e32 v78, v78
	s_nop 0
	v_sub_f32_e32 v78, 1.0, v78
	v_cndmask_b32_e64 v78, v34, v78, s[40:41]
	v_mul_f32_e32 v34, 0xbfb8aa3b, v79
	v_exp_f32_e32 v34, v34
	s_nop 0
	v_add_f32_e32 v34, 1.0, v34
	v_rcp_f32_e32 v34, v34
	s_nop 0
	v_mul_f32_e32 v79, 0xbf60028a, v34
	v_exp_f32_e32 v79, v79
	s_nop 0
	v_sub_f32_e32 v79, 1.0, v79
	v_cndmask_b32_e64 v79, v34, v79, s[40:41]
	v_mul_f32_e32 v34, 0xbfb8aa3b, v80
	v_exp_f32_e32 v34, v34
	s_nop 0
	v_add_f32_e32 v34, 1.0, v34
	v_rcp_f32_e32 v34, v34
	s_nop 0
	v_mul_f32_e32 v80, 0xbf60028a, v34
	v_exp_f32_e32 v80, v80
	s_nop 0
	v_sub_f32_e32 v80, 1.0, v80
	v_cndmask_b32_e64 v80, v34, v80, s[40:41]
	v_mul_f32_e32 v34, 0xbfb8aa3b, v81
	v_exp_f32_e32 v34, v34
	s_nop 0
	v_add_f32_e32 v34, 1.0, v34
	v_rcp_f32_e32 v34, v34
	s_nop 0
	v_mul_f32_e32 v81, 0xbf60028a, v34
	v_exp_f32_e32 v81, v81
	s_nop 0
	v_sub_f32_e32 v81, 1.0, v81
	v_cndmask_b32_e64 v81, v34, v81, s[40:41]
	v_mul_f32_e32 v34, 0xbfb8aa3b, v82
	v_exp_f32_e32 v34, v34
	s_nop 0
	v_add_f32_e32 v34, 1.0, v34
	v_rcp_f32_e32 v34, v34
	s_nop 0
	v_mul_f32_e32 v82, 0xbf60028a, v34
	v_exp_f32_e32 v82, v82
	s_nop 0
	v_sub_f32_e32 v82, 1.0, v82
	v_cndmask_b32_e64 v82, v34, v82, s[40:41]
	v_mul_f32_e32 v34, 0xbfb8aa3b, v83
	v_exp_f32_e32 v34, v34
	s_nop 0
	v_add_f32_e32 v34, 1.0, v34
	v_rcp_f32_e32 v34, v34
	s_nop 0
	v_mul_f32_e32 v83, 0xbf60028a, v34
	v_exp_f32_e32 v83, v83
	s_nop 0
	v_sub_f32_e32 v83, 1.0, v83
	v_cndmask_b32_e64 v83, v34, v83, s[40:41]
; __device__ __forceinline__ unsigned cvt_pk_bf16(float lo, float hi) { unsigned r; asm volatile("v_cvt_pk_bf16_f32 %0, %1, %2" : "=v"(r) : "v"(lo), "v"(hi)); return r; }
; __device__ __forceinline__ float fast_sigmoid(float x) { return __builtin_amdgcn_rcpf(1.0f + __builtin_amdgcn_exp2f(-x * LOG2E)); }
;     __device__ __forceinline__ void operator()(const f32x4 (&acc)[2][2][4][2], const Unit& u, int wr, int wc, int fr, int fq) const {
;     ...
;             for (int m = 0; m < 4; ++m) {
;                 bf16_t* rowp = base + (size_t)(row0 + ai * HALF + m * 16) * 1024 + col0;
; #pragma unroll
;                 for (int bj = 0; bj < 2; ++bj) {
;                     f32x4 v[2] = {acc[ai][bj][m][0], acc[ai][bj][m][1]};
;                     if (t < 2) {
;                         v[0] += bv[bj][0]; v[1] += bv[bj][1];
; #pragma unroll
;                         for (int n = 0; n < 2; ++n)
; #pragma unroll
;                             for (int j = 0; j < 4; ++j) {
;                                 float x = fast_sigmoid(v[n][j]);
;                                 if (t == 0) x = 1.0f - __builtin_amdgcn_exp2f(x * (-0.6065306597126334f * LOG2E));
;                                 v[n][j] = x;
;                             }
;                     }
;                     u32x4 w; w.x = cvt_pk_bf16(v[0][0], v[0][1]); w.y = cvt_pk_bf16(v[0][2], v[0][3]); w.z = cvt_pk_bf16(v[1][0], v[1][1]); w.w = cvt_pk_bf16(v[1][2], v[1][3]);
;                     *(u32x4*)(rowp + bj * HALF) = w;
.LBB0_409:
	v_lshlrev_b64 v[84:85], 11, v[158:159]
	v_lshl_add_u64 v[84:85], v[160:161], 0, v[84:85]
	v_cvt_pk_bf16_f32 v76, v76, v77
	v_cvt_pk_bf16_f32 v77, v78, v79
	v_cvt_pk_bf16_f32 v78, v80, v81
	v_add_co_u32_e32 v80, vcc, 0x40000, v84
	v_cvt_pk_bf16_f32 v79, v82, v83
	s_nop 1
	v_addc_co_u32_e32 v81, vcc, 0, v85, vcc
	global_store_dwordx4 v[80:81], v[76:79], off
	s_and_b64 vcc, exec, s[42:43]
	s_cbranch_vccnz .LBB0_411
	v_pk_add_f32 v[68:69], v[68:69], v[48:49]
	v_pk_add_f32 v[70:71], v[70:71], v[50:51]
	v_mul_f32_e32 v34, 0xbfb8aa3b, v68
	v_exp_f32_e32 v34, v34
	v_pk_add_f32 v[72:73], v[72:73], v[44:45]
	v_pk_add_f32 v[74:75], v[74:75], v[46:47]
	v_add_f32_e32 v34, 1.0, v34
	v_rcp_f32_e32 v34, v34
	s_nop 0
	v_mul_f32_e32 v68, 0xbf60028a, v34
	v_exp_f32_e32 v68, v68
	s_nop 0
	v_sub_f32_e32 v68, 1.0, v68
	v_cndmask_b32_e64 v68, v34, v68, s[40:41]
	v_mul_f32_e32 v34, 0xbfb8aa3b, v69
	v_exp_f32_e32 v34, v34
	s_nop 0
	v_add_f32_e32 v34, 1.0, v34
	v_rcp_f32_e32 v34, v34
	s_nop 0
	v_mul_f32_e32 v69, 0xbf60028a, v34
	v_exp_f32_e32 v69, v69
	s_nop 0
	v_sub_f32_e32 v69, 1.0, v69
	v_cndmask_b32_e64 v69, v34, v69, s[40:41]
	v_mul_f32_e32 v34, 0xbfb8aa3b, v70
	v_exp_f32_e32 v34, v34
	s_nop 0
	v_add_f32_e32 v34, 1.0, v34
	v_rcp_f32_e32 v34, v34
	s_nop 0
	v_mul_f32_e32 v70, 0xbf60028a, v34
	v_exp_f32_e32 v70, v70
	s_nop 0
	v_sub_f32_e32 v70, 1.0, v70
	v_cndmask_b32_e64 v70, v34, v70, s[40:41]
	v_mul_f32_e32 v34, 0xbfb8aa3b, v71
	v_exp_f32_e32 v34, v34
	s_nop 0
	v_add_f32_e32 v34, 1.0, v34
	v_rcp_f32_e32 v34, v34
	s_nop 0
	v_mul_f32_e32 v71, 0xbf60028a, v34
	v_exp_f32_e32 v71, v71
	s_nop 0
	v_sub_f32_e32 v71, 1.0, v71
	v_cndmask_b32_e64 v71, v34, v71, s[40:41]
	v_mul_f32_e32 v34, 0xbfb8aa3b, v72
	v_exp_f32_e32 v34, v34
	s_nop 0
	v_add_f32_e32 v34, 1.0, v34
	v_rcp_f32_e32 v34, v34
	s_nop 0
	v_mul_f32_e32 v72, 0xbf60028a, v34
	v_exp_f32_e32 v72, v72
	s_nop 0
	v_sub_f32_e32 v72, 1.0, v72
	v_cndmask_b32_e64 v72, v34, v72, s[40:41]
	v_mul_f32_e32 v34, 0xbfb8aa3b, v73
	v_exp_f32_e32 v34, v34
	s_nop 0
	v_add_f32_e32 v34, 1.0, v34
	v_rcp_f32_e32 v34, v34
	s_nop 0
	v_mul_f32_e32 v73, 0xbf60028a, v34
	v_exp_f32_e32 v73, v73
	s_nop 0
	v_sub_f32_e32 v73, 1.0, v73
	v_cndmask_b32_e64 v73, v34, v73, s[40:41]
	v_mul_f32_e32 v34, 0xbfb8aa3b, v74
	v_exp_f32_e32 v34, v34
	s_nop 0
	v_add_f32_e32 v34, 1.0, v34
	v_rcp_f32_e32 v34, v34
	s_nop 0
	v_mul_f32_e32 v74, 0xbf60028a, v34
	v_exp_f32_e32 v74, v74
	s_nop 0
	v_sub_f32_e32 v74, 1.0, v74
	v_cndmask_b32_e64 v74, v34, v74, s[40:41]
	v_mul_f32_e32 v34, 0xbfb8aa3b, v75
	v_exp_f32_e32 v34, v34
	s_nop 0
	v_add_f32_e32 v34, 1.0, v34
	v_rcp_f32_e32 v34, v34
	s_nop 0
	v_mul_f32_e32 v75, 0xbf60028a, v34
	v_exp_f32_e32 v75, v75
	s_nop 0
	v_sub_f32_e32 v75, 1.0, v75
	v_cndmask_b32_e64 v75, v34, v75, s[40:41]
.LBB0_411:
	s_mov_b64 s[4:5], 0x40000
	v_lshl_add_u64 v[76:77], v[84:85], 0, s[4:5]
	v_cvt_pk_bf16_f32 v68, v68, v69
	v_cvt_pk_bf16_f32 v69, v70, v71
	v_cvt_pk_bf16_f32 v70, v72, v73
	v_cvt_pk_bf16_f32 v71, v74, v75
	global_store_dwordx4 v[76:77], v[68:71], off offset:256
	s_and_b64 vcc, exec, s[42:43]
	s_cbranch_vccnz .LBB0_413
	v_pk_add_f32 v[60:61], v[60:61], v[56:57]
	v_pk_add_f32 v[62:63], v[62:63], v[58:59]
	v_mul_f32_e32 v34, 0xbfb8aa3b, v60
	v_exp_f32_e32 v34, v34
	v_pk_add_f32 v[64:65], v[64:65], v[52:53]
	v_pk_add_f32 v[66:67], v[66:67], v[54:55]
	v_add_f32_e32 v34, 1.0, v34
	v_rcp_f32_e32 v34, v34
	s_nop 0
	v_mul_f32_e32 v60, 0xbf60028a, v34
	v_exp_f32_e32 v60, v60
	s_nop 0
	v_sub_f32_e32 v60, 1.0, v60
	v_cndmask_b32_e64 v60, v34, v60, s[40:41]
	v_mul_f32_e32 v34, 0xbfb8aa3b, v61
	v_exp_f32_e32 v34, v34
	s_nop 0
	v_add_f32_e32 v34, 1.0, v34
	v_rcp_f32_e32 v34, v34
	s_nop 0
	v_mul_f32_e32 v61, 0xbf60028a, v34
	v_exp_f32_e32 v61, v61
	s_nop 0
	v_sub_f32_e32 v61, 1.0, v61
	v_cndmask_b32_e64 v61, v34, v61, s[40:41]
	v_mul_f32_e32 v34, 0xbfb8aa3b, v62
	v_exp_f32_e32 v34, v34
	s_nop 0
	v_add_f32_e32 v34, 1.0, v34
	v_rcp_f32_e32 v34, v34
	s_nop 0
	v_mul_f32_e32 v62, 0xbf60028a, v34
	v_exp_f32_e32 v62, v62
	s_nop 0
	v_sub_f32_e32 v62, 1.0, v62
	v_cndmask_b32_e64 v62, v34, v62, s[40:41]
	v_mul_f32_e32 v34, 0xbfb8aa3b, v63
	v_exp_f32_e32 v34, v34
	s_nop 0
	v_add_f32_e32 v34, 1.0, v34
	v_rcp_f32_e32 v34, v34
	s_nop 0
	v_mul_f32_e32 v63, 0xbf60028a, v34
	v_exp_f32_e32 v63, v63
	s_nop 0
	v_sub_f32_e32 v63, 1.0, v63
	v_cndmask_b32_e64 v63, v34, v63, s[40:41]
	v_mul_f32_e32 v34, 0xbfb8aa3b, v64
	v_exp_f32_e32 v34, v34
	s_nop 0
	v_add_f32_e32 v34, 1.0, v34
	v_rcp_f32_e32 v34, v34
	s_nop 0
	v_mul_f32_e32 v64, 0xbf60028a, v34
	v_exp_f32_e32 v64, v64
	s_nop 0
	v_sub_f32_e32 v64, 1.0, v64
	v_cndmask_b32_e64 v64, v34, v64, s[40:41]
	v_mul_f32_e32 v34, 0xbfb8aa3b, v65
	v_exp_f32_e32 v34, v34
	s_nop 0
	v_add_f32_e32 v34, 1.0, v34
	v_rcp_f32_e32 v34, v34
	s_nop 0
	v_mul_f32_e32 v65, 0xbf60028a, v34
	v_exp_f32_e32 v65, v65
	s_nop 0
	v_sub_f32_e32 v65, 1.0, v65
	v_cndmask_b32_e64 v65, v34, v65, s[40:41]
	v_mul_f32_e32 v34, 0xbfb8aa3b, v66
	v_exp_f32_e32 v34, v34
	s_nop 0
	v_add_f32_e32 v34, 1.0, v34
	v_rcp_f32_e32 v34, v34
	s_nop 0
	v_mul_f32_e32 v66, 0xbf60028a, v34
	v_exp_f32_e32 v66, v66
	s_nop 0
	v_sub_f32_e32 v66, 1.0, v66
	v_cndmask_b32_e64 v66, v34, v66, s[40:41]
	v_mul_f32_e32 v34, 0xbfb8aa3b, v67
	v_exp_f32_e32 v34, v34
	s_nop 0
	v_add_f32_e32 v34, 1.0, v34
	v_rcp_f32_e32 v34, v34
	s_nop 0
	v_mul_f32_e32 v67, 0xbf60028a, v34
	v_exp_f32_e32 v67, v67
	s_nop 0
	v_sub_f32_e32 v67, 1.0, v67
	v_cndmask_b32_e64 v67, v34, v67, s[40:41]
; __device__ __forceinline__ unsigned cvt_pk_bf16(float lo, float hi) { unsigned r; asm volatile("v_cvt_pk_bf16_f32 %0, %1, %2" : "=v"(r) : "v"(lo), "v"(hi)); return r; }
; __device__ __forceinline__ float fast_sigmoid(float x) { return __builtin_amdgcn_rcpf(1.0f + __builtin_amdgcn_exp2f(-x * LOG2E)); }
;     __device__ __forceinline__ void operator()(const f32x4 (&acc)[2][2][4][2], const Unit& u, int wr, int wc, int fr, int fq) const {
;     ...
;             for (int m = 0; m < 4; ++m) {
;                 bf16_t* rowp = base + (size_t)(row0 + ai * HALF + m * 16) * 1024 + col0;
; #pragma unroll
;                 for (int bj = 0; bj < 2; ++bj) {
;                     f32x4 v[2] = {acc[ai][bj][m][0], acc[ai][bj][m][1]};
;                     if (t < 2) {
;                         v[0] += bv[bj][0]; v[1] += bv[bj][1];
; #pragma unroll
;                         for (int n = 0; n < 2; ++n)
; #pragma unroll
;                             for (int j = 0; j < 4; ++j) {
;                                 float x = fast_sigmoid(v[n][j]);
;                                 if (t == 0) x = 1.0f - __builtin_amdgcn_exp2f(x * (-0.6065306597126334f * LOG2E));
;                                 v[n][j] = x;
;                             }
;                     }
;                     u32x4 w; w.x = cvt_pk_bf16(v[0][0], v[0][1]); w.y = cvt_pk_bf16(v[0][2], v[0][3]); w.z = cvt_pk_bf16(v[1][0], v[1][1]); w.w = cvt_pk_bf16(v[1][2], v[1][3]);
;                     *(u32x4*)(rowp + bj * HALF) = w;
.LBB0_413:
	v_lshlrev_b64 v[68:69], 11, v[158:159]
	v_lshl_add_u64 v[68:69], v[160:161], 0, v[68:69]
	v_cvt_pk_bf16_f32 v60, v60, v61
	v_cvt_pk_bf16_f32 v61, v62, v63
	v_cvt_pk_bf16_f32 v62, v64, v65
	v_add_co_u32_e32 v64, vcc, 0x48000, v68
	v_cvt_pk_bf16_f32 v63, v66, v67
	s_nop 1
	v_addc_co_u32_e32 v65, vcc, 0, v69, vcc
	global_store_dwordx4 v[64:65], v[60:63], off
	s_and_b64 vcc, exec, s[42:43]
	s_cbranch_vccnz .LBB0_415
	v_pk_add_f32 v[36:37], v[36:37], v[48:49]
	v_pk_add_f32 v[38:39], v[38:39], v[50:51]
	v_mul_f32_e32 v34, 0xbfb8aa3b, v36
	v_exp_f32_e32 v34, v34
	v_pk_add_f32 v[40:41], v[40:41], v[44:45]
	v_pk_add_f32 v[42:43], v[42:43], v[46:47]
	v_add_f32_e32 v34, 1.0, v34
	v_rcp_f32_e32 v34, v34
	s_nop 0
	v_mul_f32_e32 v36, 0xbf60028a, v34
	v_exp_f32_e32 v36, v36
	s_nop 0
	v_sub_f32_e32 v36, 1.0, v36
	v_cndmask_b32_e64 v36, v34, v36, s[40:41]
	v_mul_f32_e32 v34, 0xbfb8aa3b, v37
	v_exp_f32_e32 v34, v34
	s_nop 0
	v_add_f32_e32 v34, 1.0, v34
	v_rcp_f32_e32 v34, v34
	s_nop 0
	v_mul_f32_e32 v37, 0xbf60028a, v34
	v_exp_f32_e32 v37, v37
	s_nop 0
	v_sub_f32_e32 v37, 1.0, v37
	v_cndmask_b32_e64 v37, v34, v37, s[40:41]
	v_mul_f32_e32 v34, 0xbfb8aa3b, v38
	v_exp_f32_e32 v34, v34
	s_nop 0
	v_add_f32_e32 v34, 1.0, v34
	v_rcp_f32_e32 v34, v34
	s_nop 0
	v_mul_f32_e32 v38, 0xbf60028a, v34
	v_exp_f32_e32 v38, v38
	s_nop 0
	v_sub_f32_e32 v38, 1.0, v38
	v_cndmask_b32_e64 v38, v34, v38, s[40:41]
	v_mul_f32_e32 v34, 0xbfb8aa3b, v39
	v_exp_f32_e32 v34, v34
	s_nop 0
	v_add_f32_e32 v34, 1.0, v34
	v_rcp_f32_e32 v34, v34
	s_nop 0
	v_mul_f32_e32 v39, 0xbf60028a, v34
	v_exp_f32_e32 v39, v39
	s_nop 0
	v_sub_f32_e32 v39, 1.0, v39
	v_cndmask_b32_e64 v39, v34, v39, s[40:41]
	v_mul_f32_e32 v34, 0xbfb8aa3b, v40
	v_exp_f32_e32 v34, v34
	s_nop 0
	v_add_f32_e32 v34, 1.0, v34
	v_rcp_f32_e32 v34, v34
	s_nop 0
	v_mul_f32_e32 v40, 0xbf60028a, v34
	v_exp_f32_e32 v40, v40
	s_nop 0
	v_sub_f32_e32 v40, 1.0, v40
	v_cndmask_b32_e64 v40, v34, v40, s[40:41]
	v_mul_f32_e32 v34, 0xbfb8aa3b, v41
	v_exp_f32_e32 v34, v34
	s_nop 0
	v_add_f32_e32 v34, 1.0, v34
	v_rcp_f32_e32 v34, v34
	s_nop 0
	v_mul_f32_e32 v41, 0xbf60028a, v34
	v_exp_f32_e32 v41, v41
	s_nop 0
	v_sub_f32_e32 v41, 1.0, v41
	v_cndmask_b32_e64 v41, v34, v41, s[40:41]
	v_mul_f32_e32 v34, 0xbfb8aa3b, v42
	v_exp_f32_e32 v34, v34
	s_nop 0
	v_add_f32_e32 v34, 1.0, v34
	v_rcp_f32_e32 v34, v34
	s_nop 0
	v_mul_f32_e32 v42, 0xbf60028a, v34
	v_exp_f32_e32 v42, v42
	s_nop 0
	v_sub_f32_e32 v42, 1.0, v42
	v_cndmask_b32_e64 v42, v34, v42, s[40:41]
	v_mul_f32_e32 v34, 0xbfb8aa3b, v43
	v_exp_f32_e32 v34, v34
	s_nop 0
	v_add_f32_e32 v34, 1.0, v34
	v_rcp_f32_e32 v34, v34
	s_nop 0
	v_mul_f32_e32 v43, 0xbf60028a, v34
	v_exp_f32_e32 v43, v43
	s_nop 0
	v_sub_f32_e32 v43, 1.0, v43
	v_cndmask_b32_e64 v43, v34, v43, s[40:41]
.LBB0_415:
	s_mov_b64 s[4:5], 0x48000
	v_lshl_add_u64 v[60:61], v[68:69], 0, s[4:5]
	v_cvt_pk_bf16_f32 v36, v36, v37
	v_cvt_pk_bf16_f32 v37, v38, v39
	v_cvt_pk_bf16_f32 v38, v40, v41
	v_cvt_pk_bf16_f32 v39, v42, v43
	global_store_dwordx4 v[60:61], v[36:39], off offset:256
	s_and_b64 vcc, exec, s[42:43]
	s_cbranch_vccnz .LBB0_417
	v_pk_add_f32 v[24:25], v[24:25], v[56:57]
	v_pk_add_f32 v[26:27], v[26:27], v[58:59]
	v_mul_f32_e32 v24, 0xbfb8aa3b, v24
	v_exp_f32_e32 v24, v24
	v_mul_f32_e32 v25, 0xbfb8aa3b, v25
	v_exp_f32_e32 v25, v25
	v_mul_f32_e32 v26, 0xbfb8aa3b, v26
	v_add_f32_e32 v24, 1.0, v24
	v_rcp_f32_e32 v24, v24
	v_add_f32_e32 v25, 1.0, v25
	v_rcp_f32_e32 v25, v25
	v_exp_f32_e32 v26, v26
	v_mul_f32_e32 v34, 0xbf60028a, v24
	v_exp_f32_e32 v34, v34
	v_mul_f32_e32 v27, 0xbfb8aa3b, v27
	v_add_f32_e32 v26, 1.0, v26
	v_rcp_f32_e32 v26, v26
	v_sub_f32_e32 v34, 1.0, v34
	v_cndmask_b32_e64 v24, v24, v34, s[40:41]
	v_mul_f32_e32 v34, 0xbf60028a, v25
	v_exp_f32_e32 v34, v34
	v_exp_f32_e32 v27, v27
	v_pk_add_f32 v[28:29], v[28:29], v[52:53]
	v_pk_add_f32 v[30:31], v[30:31], v[54:55]
	v_sub_f32_e32 v34, 1.0, v34
	v_cndmask_b32_e64 v25, v25, v34, s[40:41]
	v_mul_f32_e32 v34, 0xbf60028a, v26
	v_exp_f32_e32 v34, v34
	v_add_f32_e32 v27, 1.0, v27
	v_rcp_f32_e32 v27, v27
	v_mul_f32_e32 v28, 0xbfb8aa3b, v28
	v_exp_f32_e32 v28, v28
	v_sub_f32_e32 v34, 1.0, v34
	v_cndmask_b32_e64 v26, v26, v34, s[40:41]
	v_mul_f32_e32 v34, 0xbf60028a, v27
	v_exp_f32_e32 v34, v34
	v_add_f32_e32 v28, 1.0, v28
	v_rcp_f32_e32 v28, v28
	v_mul_f32_e32 v29, 0xbfb8aa3b, v29
	v_exp_f32_e32 v29, v29
	v_sub_f32_e32 v34, 1.0, v34
	v_cndmask_b32_e64 v27, v27, v34, s[40:41]
	v_mul_f32_e32 v34, 0xbf60028a, v28
	v_exp_f32_e32 v34, v34
	v_add_f32_e32 v29, 1.0, v29
	v_rcp_f32_e32 v29, v29
	v_mul_f32_e32 v30, 0xbfb8aa3b, v30
	v_exp_f32_e32 v30, v30
	v_sub_f32_e32 v34, 1.0, v34
	v_cndmask_b32_e64 v28, v28, v34, s[40:41]
	v_mul_f32_e32 v34, 0xbf60028a, v29
	v_exp_f32_e32 v34, v34
	v_add_f32_e32 v30, 1.0, v30
	v_rcp_f32_e32 v30, v30
	v_mul_f32_e32 v31, 0xbfb8aa3b, v31
	v_exp_f32_e32 v31, v31
	v_sub_f32_e32 v34, 1.0, v34
	v_cndmask_b32_e64 v29, v29, v34, s[40:41]
	v_mul_f32_e32 v34, 0xbf60028a, v30
	v_exp_f32_e32 v34, v34
	v_add_f32_e32 v31, 1.0, v31
	v_rcp_f32_e32 v31, v31
	v_sub_f32_e32 v34, 1.0, v34
	v_cndmask_b32_e64 v30, v30, v34, s[40:41]
	v_mul_f32_e32 v34, 0xbf60028a, v31
	v_exp_f32_e32 v34, v34
	s_nop 0
	v_sub_f32_e32 v34, 1.0, v34
	v_cndmask_b32_e64 v31, v31, v34, s[40:41]
; __device__ __forceinline__ unsigned cvt_pk_bf16(float lo, float hi) { unsigned r; asm volatile("v_cvt_pk_bf16_f32 %0, %1, %2" : "=v"(r) : "v"(lo), "v"(hi)); return r; }
; __device__ __forceinline__ float fast_sigmoid(float x) { return __builtin_amdgcn_rcpf(1.0f + __builtin_amdgcn_exp2f(-x * LOG2E)); }
;     __device__ __forceinline__ void operator()(const f32x4 (&acc)[2][2][4][2], const Unit& u, int wr, int wc, int fr, int fq) const {
;     ...
;             for (int m = 0; m < 4; ++m) {
;                 bf16_t* rowp = base + (size_t)(row0 + ai * HALF + m * 16) * 1024 + col0;
; #pragma unroll
;                 for (int bj = 0; bj < 2; ++bj) {
;                     f32x4 v[2] = {acc[ai][bj][m][0], acc[ai][bj][m][1]};
;                     if (t < 2) {
;                         v[0] += bv[bj][0]; v[1] += bv[bj][1];
; #pragma unroll
;                         for (int n = 0; n < 2; ++n)
; #pragma unroll
;                             for (int j = 0; j < 4; ++j) {
;                                 float x = fast_sigmoid(v[n][j]);
;                                 if (t == 0) x = 1.0f - __builtin_amdgcn_exp2f(x * (-0.6065306597126334f * LOG2E));
;                                 v[n][j] = x;
;                             }
;                     }
;                     u32x4 w; w.x = cvt_pk_bf16(v[0][0], v[0][1]); w.y = cvt_pk_bf16(v[0][2], v[0][3]); w.z = cvt_pk_bf16(v[1][0], v[1][1]); w.w = cvt_pk_bf16(v[1][2], v[1][3]);
;                     *(u32x4*)(rowp + bj * HALF) = w;
.LBB0_417:
	v_lshlrev_b64 v[36:37], 11, v[158:159]
	v_lshl_add_u64 v[36:37], v[160:161], 0, v[36:37]
	v_cvt_pk_bf16_f32 v24, v24, v25
	v_cvt_pk_bf16_f32 v25, v26, v27
	v_cvt_pk_bf16_f32 v26, v28, v29
	v_add_co_u32_e32 v28, vcc, 0x50000, v36
	v_cvt_pk_bf16_f32 v27, v30, v31
	s_nop 1
	v_addc_co_u32_e32 v29, vcc, 0, v37, vcc
	global_store_dwordx4 v[28:29], v[24:27], off
	s_and_b64 vcc, exec, s[42:43]
	s_cbranch_vccnz .LBB0_419
	v_pk_add_f32 v[16:17], v[16:17], v[48:49]
	v_pk_add_f32 v[18:19], v[18:19], v[50:51]
	v_mul_f32_e32 v16, 0xbfb8aa3b, v16
	v_exp_f32_e32 v16, v16
	v_mul_f32_e32 v17, 0xbfb8aa3b, v17
	v_exp_f32_e32 v17, v17
	v_mul_f32_e32 v18, 0xbfb8aa3b, v18
	v_add_f32_e32 v16, 1.0, v16
	v_rcp_f32_e32 v16, v16
	v_add_f32_e32 v17, 1.0, v17
	v_rcp_f32_e32 v17, v17
	v_exp_f32_e32 v18, v18
	v_mul_f32_e32 v24, 0xbf60028a, v16
	v_exp_f32_e32 v24, v24
	v_mul_f32_e32 v19, 0xbfb8aa3b, v19
	v_add_f32_e32 v18, 1.0, v18
	v_rcp_f32_e32 v18, v18
	v_sub_f32_e32 v24, 1.0, v24
	v_cndmask_b32_e64 v16, v16, v24, s[40:41]
	v_mul_f32_e32 v24, 0xbf60028a, v17
	v_exp_f32_e32 v24, v24
	v_exp_f32_e32 v19, v19
	v_pk_add_f32 v[20:21], v[20:21], v[44:45]
	v_pk_add_f32 v[22:23], v[22:23], v[46:47]
	v_sub_f32_e32 v24, 1.0, v24
	v_cndmask_b32_e64 v17, v17, v24, s[40:41]
	v_mul_f32_e32 v24, 0xbf60028a, v18
	v_exp_f32_e32 v24, v24
	v_add_f32_e32 v19, 1.0, v19
	v_rcp_f32_e32 v19, v19
	v_mul_f32_e32 v20, 0xbfb8aa3b, v20
	v_exp_f32_e32 v20, v20
	v_sub_f32_e32 v24, 1.0, v24
	v_cndmask_b32_e64 v18, v18, v24, s[40:41]
	v_mul_f32_e32 v24, 0xbf60028a, v19
	v_exp_f32_e32 v24, v24
	v_add_f32_e32 v20, 1.0, v20
	v_rcp_f32_e32 v20, v20
	v_mul_f32_e32 v21, 0xbfb8aa3b, v21
	v_exp_f32_e32 v21, v21
	v_sub_f32_e32 v24, 1.0, v24
	v_cndmask_b32_e64 v19, v19, v24, s[40:41]
	v_mul_f32_e32 v24, 0xbf60028a, v20
	v_exp_f32_e32 v24, v24
	v_add_f32_e32 v21, 1.0, v21
	v_rcp_f32_e32 v21, v21
	v_mul_f32_e32 v22, 0xbfb8aa3b, v22
	v_exp_f32_e32 v22, v22
	v_sub_f32_e32 v24, 1.0, v24
	v_cndmask_b32_e64 v20, v20, v24, s[40:41]
	v_mul_f32_e32 v24, 0xbf60028a, v21
	v_exp_f32_e32 v24, v24
	v_add_f32_e32 v22, 1.0, v22
	v_rcp_f32_e32 v22, v22
	v_mul_f32_e32 v23, 0xbfb8aa3b, v23
	v_exp_f32_e32 v23, v23
	v_sub_f32_e32 v24, 1.0, v24
	v_cndmask_b32_e64 v21, v21, v24, s[40:41]
	v_mul_f32_e32 v24, 0xbf60028a, v22
	v_exp_f32_e32 v24, v24
	v_add_f32_e32 v23, 1.0, v23
	v_rcp_f32_e32 v23, v23
	v_sub_f32_e32 v24, 1.0, v24
	v_cndmask_b32_e64 v22, v22, v24, s[40:41]
	v_mul_f32_e32 v24, 0xbf60028a, v23
	v_exp_f32_e32 v24, v24
	s_nop 0
	v_sub_f32_e32 v24, 1.0, v24
	v_cndmask_b32_e64 v23, v23, v24, s[40:41]
; __device__ __forceinline__ unsigned cvt_pk_bf16(float lo, float hi) { unsigned r; asm volatile("v_cvt_pk_bf16_f32 %0, %1, %2" : "=v"(r) : "v"(lo), "v"(hi)); return r; }
; __device__ __forceinline__ float fast_sigmoid(float x) { return __builtin_amdgcn_rcpf(1.0f + __builtin_amdgcn_exp2f(-x * LOG2E)); }
;     __device__ __forceinline__ void operator()(const f32x4 (&acc)[2][2][4][2], const Unit& u, int wr, int wc, int fr, int fq) const {
;     ...
;             for (int m = 0; m < 4; ++m) {
;                 bf16_t* rowp = base + (size_t)(row0 + ai * HALF + m * 16) * 1024 + col0;
; #pragma unroll
;                 for (int bj = 0; bj < 2; ++bj) {
;                     f32x4 v[2] = {acc[ai][bj][m][0], acc[ai][bj][m][1]};
;                     if (t < 2) {
;                         v[0] += bv[bj][0]; v[1] += bv[bj][1];
; #pragma unroll
;                         for (int n = 0; n < 2; ++n)
; #pragma unroll
;                             for (int j = 0; j < 4; ++j) {
;                                 float x = fast_sigmoid(v[n][j]);
;                                 if (t == 0) x = 1.0f - __builtin_amdgcn_exp2f(x * (-0.6065306597126334f * LOG2E));
;                                 v[n][j] = x;
;                             }
;                     }
;                     u32x4 w; w.x = cvt_pk_bf16(v[0][0], v[0][1]); w.y = cvt_pk_bf16(v[0][2], v[0][3]); w.z = cvt_pk_bf16(v[1][0], v[1][1]); w.w = cvt_pk_bf16(v[1][2], v[1][3]);
;                     *(u32x4*)(rowp + bj * HALF) = w;
.LBB0_419:
	s_mov_b64 s[4:5], 0x50000
	v_lshl_add_u64 v[24:25], v[36:37], 0, s[4:5]
	v_cvt_pk_bf16_f32 v16, v16, v17
	v_cvt_pk_bf16_f32 v17, v18, v19
	v_cvt_pk_bf16_f32 v18, v20, v21
	v_cvt_pk_bf16_f32 v19, v22, v23
	global_store_dwordx4 v[24:25], v[16:19], off offset:256
	s_and_b64 vcc, exec, s[42:43]
	s_cbranch_vccnz .LBB0_421
	v_pk_add_f32 v[8:9], v[8:9], v[56:57]
	v_pk_add_f32 v[10:11], v[10:11], v[58:59]
	v_mul_f32_e32 v8, 0xbfb8aa3b, v8
	v_exp_f32_e32 v8, v8
	v_mul_f32_e32 v9, 0xbfb8aa3b, v9
	v_mul_f32_e32 v10, 0xbfb8aa3b, v10
	v_exp_f32_e32 v9, v9
	v_add_f32_e32 v8, 1.0, v8
	v_rcp_f32_e32 v8, v8
	v_exp_f32_e32 v10, v10
	v_add_f32_e32 v9, 1.0, v9
	v_rcp_f32_e32 v9, v9
	v_mul_f32_e32 v16, 0xbf60028a, v8
	v_exp_f32_e32 v16, v16
	v_add_f32_e32 v10, 1.0, v10
	v_pk_add_f32 v[12:13], v[12:13], v[52:53]
	v_rcp_f32_e32 v10, v10
	v_mul_f32_e32 v11, 0xbfb8aa3b, v11
	v_exp_f32_e32 v11, v11
	v_mul_f32_e32 v12, 0xbfb8aa3b, v12
	v_sub_f32_e32 v16, 1.0, v16
	v_exp_f32_e32 v12, v12
	v_cndmask_b32_e64 v8, v8, v16, s[40:41]
	v_mul_f32_e32 v16, 0xbf60028a, v9
	v_exp_f32_e32 v16, v16
	v_mul_f32_e32 v17, 0xbf60028a, v10
	v_exp_f32_e32 v17, v17
	v_add_f32_e32 v11, 1.0, v11
	v_rcp_f32_e32 v11, v11
	v_add_f32_e32 v12, 1.0, v12
	v_pk_add_f32 v[14:15], v[14:15], v[54:55]
	v_rcp_f32_e32 v12, v12
	v_mul_f32_e32 v13, 0xbfb8aa3b, v13
	v_sub_f32_e32 v16, 1.0, v16
	v_exp_f32_e32 v13, v13
	v_mul_f32_e32 v14, 0xbfb8aa3b, v14
	v_cndmask_b32_e64 v9, v9, v16, s[40:41]
	v_sub_f32_e32 v16, 1.0, v17
	v_exp_f32_e32 v14, v14
	v_mul_f32_e32 v15, 0xbfb8aa3b, v15
	v_cndmask_b32_e64 v10, v10, v16, s[40:41]
	v_mul_f32_e32 v16, 0xbf60028a, v11
	v_exp_f32_e32 v15, v15
	v_exp_f32_e32 v16, v16
	v_mul_f32_e32 v17, 0xbf60028a, v12
	v_exp_f32_e32 v17, v17
	v_add_f32_e32 v13, 1.0, v13
	v_rcp_f32_e32 v13, v13
	v_add_f32_e32 v14, 1.0, v14
	v_rcp_f32_e32 v14, v14
	v_add_f32_e32 v15, 1.0, v15
	v_sub_f32_e32 v16, 1.0, v16
	v_rcp_f32_e32 v15, v15
	v_cndmask_b32_e64 v11, v11, v16, s[40:41]
	v_sub_f32_e32 v16, 1.0, v17
	v_cndmask_b32_e64 v12, v12, v16, s[40:41]
	v_mul_f32_e32 v16, 0xbf60028a, v13
	v_exp_f32_e32 v16, v16
	v_mul_f32_e32 v17, 0xbf60028a, v14
	v_exp_f32_e32 v17, v17
	v_mul_f32_e32 v18, 0xbf60028a, v15
	v_exp_f32_e32 v18, v18
	v_sub_f32_e32 v16, 1.0, v16
	v_cndmask_b32_e64 v13, v13, v16, s[40:41]
	v_sub_f32_e32 v16, 1.0, v17
	v_cndmask_b32_e64 v14, v14, v16, s[40:41]
	v_sub_f32_e32 v16, 1.0, v18
	v_cndmask_b32_e64 v15, v15, v16, s[40:41]
.LBB0_421:
	v_lshlrev_b64 v[16:17], 11, v[158:159]
	v_lshl_add_u64 v[16:17], v[160:161], 0, v[16:17]
	v_cvt_pk_bf16_f32 v8, v8, v9
	v_cvt_pk_bf16_f32 v9, v10, v11
	v_cvt_pk_bf16_f32 v10, v12, v13
	v_add_co_u32_e32 v12, vcc, 0x58000, v16
	v_cvt_pk_bf16_f32 v11, v14, v15
	s_nop 1
	v_addc_co_u32_e32 v13, vcc, 0, v17, vcc
	global_store_dwordx4 v[12:13], v[8:11], off
	s_and_b64 vcc, exec, s[42:43]
	s_cbranch_vccnz .LBB0_423
	v_pk_add_f32 v[0:1], v[0:1], v[48:49]
	v_pk_add_f32 v[2:3], v[2:3], v[50:51]
	v_mul_f32_e32 v0, 0xbfb8aa3b, v0
	v_exp_f32_e32 v0, v0
	v_mul_f32_e32 v1, 0xbfb8aa3b, v1
	v_mul_f32_e32 v2, 0xbfb8aa3b, v2
	v_exp_f32_e32 v1, v1
	v_add_f32_e32 v0, 1.0, v0
	v_rcp_f32_e32 v0, v0
	v_exp_f32_e32 v2, v2
	v_add_f32_e32 v1, 1.0, v1
	v_rcp_f32_e32 v1, v1
	v_mul_f32_e32 v8, 0xbf60028a, v0
	v_exp_f32_e32 v8, v8
	v_add_f32_e32 v2, 1.0, v2
	v_pk_add_f32 v[4:5], v[4:5], v[44:45]
	v_rcp_f32_e32 v2, v2
	v_mul_f32_e32 v3, 0xbfb8aa3b, v3
	v_exp_f32_e32 v3, v3
	v_mul_f32_e32 v4, 0xbfb8aa3b, v4
	v_sub_f32_e32 v8, 1.0, v8
	v_exp_f32_e32 v4, v4
	v_cndmask_b32_e64 v0, v0, v8, s[40:41]
	v_mul_f32_e32 v8, 0xbf60028a, v1
	v_exp_f32_e32 v8, v8
	v_mul_f32_e32 v9, 0xbf60028a, v2
	v_exp_f32_e32 v9, v9
	v_add_f32_e32 v3, 1.0, v3
	v_rcp_f32_e32 v3, v3
	v_add_f32_e32 v4, 1.0, v4
	v_pk_add_f32 v[6:7], v[6:7], v[46:47]
	v_rcp_f32_e32 v4, v4
	v_mul_f32_e32 v5, 0xbfb8aa3b, v5
	v_sub_f32_e32 v8, 1.0, v8
	v_exp_f32_e32 v5, v5
	v_mul_f32_e32 v6, 0xbfb8aa3b, v6
	v_cndmask_b32_e64 v1, v1, v8, s[40:41]
	v_sub_f32_e32 v8, 1.0, v9
	v_exp_f32_e32 v6, v6
	v_mul_f32_e32 v7, 0xbfb8aa3b, v7
	v_cndmask_b32_e64 v2, v2, v8, s[40:41]
	v_mul_f32_e32 v8, 0xbf60028a, v3
	v_exp_f32_e32 v7, v7
	v_exp_f32_e32 v8, v8
	v_mul_f32_e32 v9, 0xbf60028a, v4
	v_exp_f32_e32 v9, v9
	v_add_f32_e32 v5, 1.0, v5
	v_rcp_f32_e32 v5, v5
	v_add_f32_e32 v6, 1.0, v6
	v_rcp_f32_e32 v6, v6
	v_add_f32_e32 v7, 1.0, v7
	v_sub_f32_e32 v8, 1.0, v8
	v_rcp_f32_e32 v7, v7
	v_cndmask_b32_e64 v3, v3, v8, s[40:41]
	v_sub_f32_e32 v8, 1.0, v9
	v_cndmask_b32_e64 v4, v4, v8, s[40:41]
	v_mul_f32_e32 v8, 0xbf60028a, v5
	v_exp_f32_e32 v8, v8
	v_mul_f32_e32 v9, 0xbf60028a, v6
	v_exp_f32_e32 v9, v9
	v_mul_f32_e32 v10, 0xbf60028a, v7
	v_exp_f32_e32 v10, v10
	v_sub_f32_e32 v8, 1.0, v8
	v_cndmask_b32_e64 v5, v5, v8, s[40:41]
	v_sub_f32_e32 v8, 1.0, v9
	v_cndmask_b32_e64 v6, v6, v8, s[40:41]
	v_sub_f32_e32 v8, 1.0, v10
	v_cndmask_b32_e64 v7, v7, v8, s[40:41]

; __device__ __forceinline__ void attn_phase(const bf16* Q, const bf16* K, const bf16* V, bf16* O, int gw, int ngw, int lane) {
;     ...
;         const bf16* qp = Q + (rowb + t0 + fr) * 1024 + h * 64 + fq * 8;
;         const bf16x8 qb0 = *(const bf16x8*)(qp), qb1 = *(const bf16x8*)(qp + 32);
;         f32x4 o[4];
; #pragma unroll
;         for (int dt = 0; dt < 4; ++dt) o[dt] = (f32x4){0.f, 0.f, 0.f, 0.f};
;         float carry = 1.f;
;         const int tq = t0 + fr;
;         bf16x8 kn0, kn1; unsigned short vn[4][4];
;     ...
;         ATT_LOAD(t0 + 14)
;         for (int s_hi = t0 + 14; s_hi >= 0; s_hi -= 16) {
;             const bf16x8 ka0 = kn0, ka1 = kn1;
;             unsigned short vv[4][4];
; #pragma unroll
;             for (int j = 0; j < 4; ++j)
; #pragma unroll
;                 for (int dt = 0; dt < 4; ++dt) vv[dt][j] = vn[dt][j];
;             ATT_LOAD(s_hi - 16)
;             f32x4 z = (f32x4){0.f, 0.f, 0.f, 0.f};
;             z = __builtin_amdgcn_mfma_f32_16x16x32_bf16(ka0, qb0, z, 0, 0, 0);
;             z = __builtin_amdgcn_mfma_f32_16x16x32_bf16(ka1, qb1, z, 0, 0, 0);
;             float dd[4], sg[4];
; #pragma unroll
;             for (int i = 0; i < 4; ++i) {
;                 const int s = s_hi - (4 * fq + i);
;                 const bool valid = (s >= 0) && (s < tq);
;                 const float e = __builtin_amdgcn_exp2f(fminf(z[i], 100.f));
;                 const float d = __builtin_amdgcn_rcpf(1.0f + e);
;                 dd[i] = valid ? d : 1.f; sg[i] = valid ? e * d : 0.f;
;             }
;             const float c1 = dd[0], c2 = c1 * dd[1], c3 = c2 * dd[2], g = c3 * dd[3];
;             const float g0 = __shfl(g, fr), g1 = __shfl(g, fr + 16), g2 = __shfl(g, fr + 32), g3 = __shfl(g, fr + 48);
;             float pre = carry;
;             if (fq > 0) pre *= g0;
;             if (fq > 1) pre *= g1;
;             if (fq > 2) pre *= g2;
;             carry = carry * ((g0 * g1) * (g2 * g3));
;             const float p0 = sg[0] * pre, p1 = sg[1] * (pre * c1), p2 = sg[2] * (pre * c2), p3 = sg[3] * (pre * c3);
;             bf16x8 pb; { const unsigned w0 = pk2(p0, p1), w1 = pk2(p2, p3); pb[0] = (short)(w0 & 0xffff); pb[1] = (short)(w0 >> 16); pb[2] = (short)(w1 & 0xffff); pb[3] = (short)(w1 >> 16); pb[4] = 0; pb[5] = 0; pb[6] = 0; pb[7] = 0; }
.LBB0_2224:
	s_ashr_i32 s4, s1, 13
	s_lshl_b32 s5, s1, 4
	s_and_b32 s6, s5, 0x1ff0
	s_ashr_i32 s5, s4, 31
	s_lshl_b64 s[4:5], s[4:5], 13
	v_or_b32_e32 v58, s6, v59
	v_or_b32_e32 v66, s4, v58
	v_mov_b32_e32 v67, s5
	s_lshr_b32 s7, s1, 3
	v_lshlrev_b64 v[0:1], 11, v[66:67]
	s_and_b32 s10, s7, 0x3c0
	v_lshl_add_u64 v[0:1], s[46:47], 0, v[0:1]
	s_lshl_b32 s92, s10, 1
	v_lshl_add_u64 v[0:1], v[0:1], 0, s[92:93]
	v_mov_b32_e32 v53, v236
	v_lshl_add_u64 v[0:1], v[0:1], 0, v[52:53]
	global_load_dwordx4 v[36:39], v[0:1], off
	global_load_dwordx4 v[40:43], v[0:1], off offset:64
	s_or_b32 s11, s6, 14
	v_sub_u32_e32 v0, s11, v59
	v_max_i32_e32 v0, 0, v0
	v_mov_b32_e32 v1, v236
	v_lshl_add_u64 v[0:1], s[4:5], 0, v[0:1]
	v_lshlrev_b64 v[0:1], 11, v[0:1]
	v_lshl_add_u64 v[0:1], s[48:49], 0, v[0:1]
	v_lshl_add_u64 v[0:1], v[0:1], 0, s[92:93]
	v_lshl_add_u64 v[64:65], v[0:1], 0, v[52:53]
	global_load_dwordx4 v[106:109], v[64:65], off
	global_load_dwordx4 v[110:113], v[64:65], off offset:64
	v_sub_u32_e32 v0, s11, v48
	v_lshlrev_b64 v[56:57], 10, v[66:67]
	v_or_b32_e32 v66, s4, v0
	v_sub_u32_e32 v0, s11, v74
	v_or_b32_e32 v68, s4, v0
	v_sub_u32_e32 v0, s11, v50
	v_or_b32_e32 v70, s4, v0
	v_sub_u32_e32 v0, s11, v49
	v_mov_b32_e32 v12, 0
	v_lshl_add_u64 v[60:61], v[44:45], 0, s[92:93]
	v_mov_b32_e32 v69, s5
	v_mov_b32_e32 v71, s5
	v_max_i32_e32 v72, 0, v0
	v_lshl_add_u64 v[62:63], v[46:47], 0, s[92:93]
	v_mov_b32_e32 v51, v58
	v_mov_b32_e32 v53, 1.0
	v_mov_b32_e32 v13, v12
	v_mov_b32_e32 v14, v12
	v_mov_b32_e32 v15, v12
	v_mov_b32_e32 v0, v12
	v_mov_b32_e32 v1, v12
	v_mov_b32_e32 v2, v12
	v_mov_b32_e32 v3, v12
	v_mov_b32_e32 v4, v12
	v_mov_b32_e32 v5, v12
	v_mov_b32_e32 v6, v12
	v_mov_b32_e32 v7, v12
	v_mov_b32_e32 v8, v12
	v_mov_b32_e32 v9, v12
	v_mov_b32_e32 v10, v12
	v_mov_b32_e32 v11, v12
	v_mov_b32_e32 v32, v12
	v_mov_b32_e32 v35, v12
	v_mov_b32_e32 v33, v12
	s_branch .LBB0_2226
.LBB0_2225:
	v_mov_b32_e32 v73, v236
	v_lshl_add_u64 v[0:1], s[4:5], 0, v[72:73]
	v_lshlrev_b64 v[0:1], 11, v[0:1]
	v_lshlrev_b64 v[4:5], 11, v[68:69]
	v_lshl_add_u64 v[0:1], v[60:61], 0, v[0:1]
	v_lshlrev_b64 v[2:3], 11, v[70:71]
	v_lshl_add_u64 v[32:33], v[60:61], 0, v[4:5]
	v_lshlrev_b64 v[4:5], 11, v[66:67]
	v_lshl_add_u64 v[2:3], v[60:61], 0, v[2:3]
	v_lshl_add_u64 v[34:35], v[60:61], 0, v[4:5]
	global_load_ushort v55, v[0:1], off offset:96
	global_load_ushort v73, v[2:3], off offset:96
	global_load_ushort v82, v[32:33], off offset:96
	global_load_ushort v83, v[34:35], off offset:96
	global_load_ushort v8, v[0:1], off offset:64
	global_load_ushort v9, v[2:3], off offset:64
	global_load_ushort v10, v[32:33], off offset:64
	global_load_ushort v11, v[34:35], off offset:64
	global_load_ushort v4, v[0:1], off offset:32
	global_load_ushort v5, v[2:3], off offset:32
	global_load_ushort v6, v[32:33], off offset:32
	global_load_ushort v7, v[34:35], off offset:32
	s_nop 0
	global_load_ushort v0, v[0:1], off
	s_nop 0
	global_load_ushort v1, v[2:3], off
	global_load_ushort v92, v[32:33], off
	global_load_ushort v93, v[34:35], off
	s_add_i32 s12, s11, -16
	v_add_u32_e32 v2, s12, v78
	v_max_i32_e32 v2, 0, v2
	v_mov_b32_e32 v3, v236
	v_lshl_add_u64 v[2:3], s[4:5], 0, v[2:3]
	v_lshlrev_b64 v[2:3], 11, v[2:3]
	v_add_u32_e32 v32, s11, v77
	v_lshl_add_u64 v[64:65], v[62:63], 0, v[2:3]
	v_add_u32_e32 v2, -16, v32
	v_max_i32_e32 v2, 0, v2
	v_mov_b32_e32 v3, v236
	v_lshl_add_u64 v[66:67], s[4:5], 0, v[2:3]
	v_subrev_u32_e32 v2, 17, v32
	v_max_i32_e32 v2, 0, v2
	v_lshl_add_u64 v[68:69], s[4:5], 0, v[2:3]
	v_add_u32_e32 v2, s12, v76
	v_max_i32_e32 v2, 0, v2
	v_lshl_add_u64 v[70:71], s[4:5], 0, v[2:3]
	v_add_u32_e32 v2, s12, v75
	v_max_i32_e32 v72, 0, v2
	v_cmp_lt_u32_e32 vcc, v32, v58
	v_sub_u32_e32 v35, s11, v50
	v_cmp_lt_u32_e64 s[44:45], v35, v58
	s_pack_ll_b32_b16 s6, 0, 0
	v_mov_b32_e32 v237, v236
	s_mov_b64 s[8:9], 0
	s_waitcnt vmcnt(16)
	v_mfma_f32_16x16x32_bf16 v[84:87], v[106:109], v[36:39], 0
	v_mfma_f32_16x16x32_bf16 v[84:87], v[110:113], v[40:43], v[84:87]
	global_load_dwordx4 v[106:109], v[64:65], off
	global_load_dwordx4 v[110:113], v[64:65], off offset:64
	s_nop 7
	v_max_f32_e32 v2, v84, v84
	v_min_f32_e32 v2, 0x42c80000, v2
	v_exp_f32_e32 v2, v2
	v_sub_u32_e32 v84, s11, v49
	s_mov_b32 s11, s12
	v_add_f32_e32 v3, 1.0, v2
	v_rcp_f32_e32 v3, v3
	s_nop 0
	v_mul_f32_e32 v2, v2, v3
	v_cndmask_b32_e32 v89, 0, v2, vcc
	v_add_u32_e32 v2, -1, v32
	v_cndmask_b32_e32 v88, 1.0, v3, vcc
	v_cmp_lt_u32_e32 vcc, v2, v58
	v_max_f32_e32 v2, v85, v85
	v_min_f32_e32 v2, 0x42c80000, v2
	v_exp_f32_e32 v2, v2
	v_or_b32_e32 v85, v232, v59
	v_lshlrev_b32_e32 v85, 2, v85
	v_add_f32_e32 v3, 1.0, v2
	v_rcp_f32_e32 v3, v3
	s_nop 0
	v_mul_f32_e32 v2, v2, v3
	v_cndmask_b32_e32 v90, 0, v2, vcc
	v_max_f32_e32 v2, v86, v86
	v_min_f32_e32 v2, 0x42c80000, v2
	v_exp_f32_e32 v2, v2
	v_cndmask_b32_e32 v34, 1.0, v3, vcc
	v_cmp_lt_u32_e32 vcc, v84, v51
	v_add_f32_e32 v3, 1.0, v2
	v_rcp_f32_e32 v32, v3
	v_max_f32_e32 v3, v87, v87
	v_min_f32_e32 v3, 0x42c80000, v3
	v_exp_f32_e32 v3, v3
	v_cndmask_b32_e64 v35, 1.0, v32, s[44:45]
	v_add_f32_e32 v33, 1.0, v3
	v_rcp_f32_e32 v33, v33
	s_nop 0
	v_pk_mul_f32 v[2:3], v[2:3], v[32:33]
	v_mul_f32_e32 v32, v88, v34
	v_cndmask_b32_e32 v84, 1.0, v33, vcc
	v_mul_f32_e32 v33, v35, v32
	v_mul_f32_e32 v86, v84, v33
	ds_bpermute_b32 v34, v85, v86
	ds_bpermute_b32 v84, v79, v86
	ds_bpermute_b32 v35, v80, v86
	ds_bpermute_b32 v85, v81, v86
	v_cndmask_b32_e32 v3, 0, v3, vcc
	s_waitcnt lgkmcnt(3)
	v_mul_f32_e32 v86, v53, v34
	v_cndmask_b32_e64 v86, v86, v53, s[38:39]
	s_waitcnt lgkmcnt(2)
	v_mul_f32_e32 v87, v86, v84
	v_cndmask_b32_e64 v86, v86, v87, s[40:41]
	s_waitcnt lgkmcnt(1)
	v_mul_f32_e32 v87, v86, v35
	v_cndmask_b32_e64 v86, v86, v87, s[42:43]
	s_waitcnt lgkmcnt(0)
	v_pk_mul_f32 v[34:35], v[34:35], v[84:85]
	v_mul_f32_e32 v84, v88, v86
	v_mul_f32_e32 v34, v34, v35
	v_mul_f32_e32 v35, v89, v86
	v_mul_f32_e32 v84, v90, v84
	v_pk_mul_f32 v[32:33], v[32:33], v[86:87] op_sel_hi:[1,0]
	v_cvt_pk_bf16_f32 v234, v35, v84
	s_waitcnt vmcnt(2)
	v_perm_b32 v84, v92, v93, s0
	v_perm_b32 v85, v0, v1, s0
	v_mov_b32_e32 v86, s6
	v_mov_b32_e32 v87, s6
	v_cndmask_b32_e64 v2, 0, v2, s[44:45]
	v_pk_mul_f32 v[2:3], v[2:3], v[32:33]
	v_mul_f32_e32 v53, v53, v34
	v_cvt_pk_bf16_f32 v235, v2, v3
	v_cmp_neq_f32_e32 vcc, 0, v53
	s_cmp_eq_u64 vcc, 0
	v_mfma_f32_16x16x32_bf16 v[0:3], v[84:87], v[234:237], v[16:19]
	v_perm_b32 v84, v6, v7, s0
	v_perm_b32 v85, v4, v5, s0
	s_cselect_b64 s[6:7], -1, 0
	s_nop 0
	v_mfma_f32_16x16x32_bf16 v[4:7], v[84:87], v[234:237], v[20:23]
	v_perm_b32 v84, v10, v11, s0
	v_perm_b32 v85, v8, v9, s0
	s_nop 1
	v_mfma_f32_16x16x32_bf16 v[8:11], v[84:87], v[234:237], v[24:27]
	v_perm_b32 v84, v82, v83, s0
	v_perm_b32 v85, v55, v73, s0
	s_nop 1
	v_mfma_f32_16x16x32_bf16 v[12:15], v[84:87], v[234:237], v[12:15]
	s_nop 7
	v_mov_b32_e32 v32, v13
	v_mov_b32_e32 v35, v14
	v_mov_b32_e32 v33, v15
	s_andn2_b64 vcc, exec, s[6:7]
	s_cbranch_vccz .LBB0_2228
